# v28 + P2 sample gather loop: all 32 K/V loads of a chunk issued back-to-back as early as register deps allow (scalar running base + lane offset VGPR), vmcnt and s_nop re-derived
# speedup vs baseline: 1.0197x; 1.0060x over previous
.LBB0_347:
	v_lshlrev_b32_e32 v254, 2, v68
	v_mov_b32_dpp v14, v76 quad_perm:[1,0,3,2] row_mask:0xf bank_mask:0xf bound_ctrl:1
	v_max_f32_e32 v14, v14, v14
	v_max_f32_e32 v15, v76, v76
	v_max_f32_e32 v14, v15, v14
	s_nop 1
	v_mov_b32_dpp v15, v14 quad_perm:[2,3,0,1] row_mask:0xf bank_mask:0xf bound_ctrl:1
	v_max_f32_e32 v15, v15, v15
	v_max_f32_e32 v14, v14, v15
	s_nop 1
	v_mov_b32_dpp v15, v14 row_half_mirror row_mask:0xf bank_mask:0xf bound_ctrl:1
	v_max_f32_e32 v15, v15, v15
	v_max_f32_e32 v14, v14, v15
	s_nop 1
	v_mov_b32_dpp v15, v14 row_mirror row_mask:0xf bank_mask:0xf bound_ctrl:1
	v_max_f32_e32 v15, v15, v15
	v_max_f32_e32 v14, v14, v15
	v_mov_b32_e32 v15, v14
	s_nop 1
	v_permlane16_swap_b32_e32 v14, v15
	v_max_f32_e32 v15, v15, v15
	v_max_f32_e32 v14, v14, v14
	v_max_f32_e32 v14, v14, v15
	v_mov_b32_e32 v15, v14
	s_nop 1
	v_permlane32_swap_b32_e32 v14, v15
	v_max_f32_e32 v15, v15, v15
	v_max_f32_e32 v14, v14, v14
	v_max_f32_e32 v14, v14, v15
	v_cmp_eq_f32_e32 vcc, v76, v14
	s_ff1_i32_b64 s0, vcc
	s_add_i32 s0, s0, 1
	s_cmp_lg_u64 vcc, 0
	s_cselect_b32 s0, s0, 0
	s_add_i32 s0, s0, -1
	s_and_b32 s0, s0, 31
	s_lshl_b32 s1, s0, 1
	s_waitcnt vmcnt(3)
	v_readlane_b32 s6, v71, s1
	s_ashr_i32 s7, s6, 31
	s_lshl_b64 s[6:7], s[6:7], 16
	s_lshl_b64 s[98:99], s[6:7], 2
	s_add_u32 s98, s98, s84
	s_addc_u32 s99, s99, s85
	global_load_dwordx4 v[80:83], v254, s[98:99] nt
	s_add_u32 s98, s98, 0x2000
	s_addc_u32 s99, s99, 0
	global_load_dwordx4 v[84:87], v254, s[98:99] nt
	s_add_u32 s98, s98, 0x2000
	s_addc_u32 s99, s99, 0
	global_load_dwordx4 v[88:91], v254, s[98:99] nt
	s_add_u32 s98, s98, 0x2000
	s_addc_u32 s99, s99, 0
	global_load_dwordx4 v[92:95], v254, s[98:99] nt
	s_add_u32 s98, s98, 0x2000
	s_addc_u32 s99, s99, 0
	global_load_dwordx4 v[96:99], v254, s[98:99] nt
	s_add_u32 s98, s98, 0x2000
	s_addc_u32 s99, s99, 0
	global_load_dwordx4 v[100:103], v254, s[98:99] nt
	s_add_u32 s98, s98, 0x2000
	s_addc_u32 s99, s99, 0
	global_load_dwordx4 v[104:107], v254, s[98:99] nt
	s_add_u32 s98, s98, 0x2000
	s_addc_u32 s99, s99, 0
	global_load_dwordx4 v[108:111], v254, s[98:99] nt
	s_add_u32 s98, s98, 0x2000
	s_addc_u32 s99, s99, 0
	global_load_dwordx4 v[112:115], v254, s[98:99] nt
	s_add_u32 s98, s98, 0x2000
	s_addc_u32 s99, s99, 0
	global_load_dwordx4 v[116:119], v254, s[98:99] nt
	s_add_u32 s98, s98, 0x2000
	s_addc_u32 s99, s99, 0
	global_load_dwordx4 v[120:123], v254, s[98:99] nt
	s_add_u32 s98, s98, 0x2000
	s_addc_u32 s99, s99, 0
	global_load_dwordx4 v[124:127], v254, s[98:99] nt
	s_add_u32 s98, s98, 0x2000
	s_addc_u32 s99, s99, 0
	global_load_dwordx4 v[128:131], v254, s[98:99] nt
	s_add_u32 s98, s98, 0x2000
	s_addc_u32 s99, s99, 0
	global_load_dwordx4 v[132:135], v254, s[98:99] nt
	s_add_u32 s98, s98, 0x2000
	s_addc_u32 s99, s99, 0
	global_load_dwordx4 v[136:139], v254, s[98:99] nt
	s_add_u32 s98, s98, 0x2000
	s_addc_u32 s99, s99, 0
	global_load_dwordx4 v[140:143], v254, s[98:99] nt
	s_lshl_b64 s[100:101], s[6:7], 2
	s_add_u32 s100, s100, s86
	s_addc_u32 s101, s101, s87
	global_load_dwordx4 v[144:147], v254, s[100:101] nt
	s_add_u32 s100, s100, 0x2000
	s_addc_u32 s101, s101, 0
	global_load_dwordx4 v[148:151], v254, s[100:101] nt
	s_add_u32 s100, s100, 0x2000
	s_addc_u32 s101, s101, 0
	global_load_dwordx4 v[152:155], v254, s[100:101] nt
	s_add_u32 s100, s100, 0x2000
	s_addc_u32 s101, s101, 0
	global_load_dwordx4 v[62:65], v254, s[100:101] nt
	s_add_u32 s100, s100, 0x2000
	s_addc_u32 s101, s101, 0
	global_load_dwordx4 v[58:61], v254, s[100:101] nt
	s_add_u32 s100, s100, 0x2000
	s_addc_u32 s101, s101, 0
	global_load_dwordx4 v[54:57], v254, s[100:101] nt
	s_add_u32 s100, s100, 0x2000
	s_addc_u32 s101, s101, 0
	global_load_dwordx4 v[50:53], v254, s[100:101] nt
	s_add_u32 s100, s100, 0x2000
	s_addc_u32 s101, s101, 0
	global_load_dwordx4 v[46:49], v254, s[100:101] nt
	s_add_u32 s100, s100, 0x2000
	s_addc_u32 s101, s101, 0
	global_load_dwordx4 v[42:45], v254, s[100:101] nt
	s_add_u32 s100, s100, 0x2000
	s_addc_u32 s101, s101, 0
	global_load_dwordx4 v[38:41], v254, s[100:101] nt
	s_add_u32 s100, s100, 0x2000
	s_addc_u32 s101, s101, 0
	global_load_dwordx4 v[34:37], v254, s[100:101] nt
	s_add_u32 s100, s100, 0x2000
	s_addc_u32 s101, s101, 0
	global_load_dwordx4 v[30:33], v254, s[100:101] nt
	s_add_u32 s100, s100, 0x2000
	s_addc_u32 s101, s101, 0
	global_load_dwordx4 v[26:29], v254, s[100:101] nt
	s_add_u32 s100, s100, 0x2000
	s_addc_u32 s101, s101, 0
	global_load_dwordx4 v[22:25], v254, s[100:101] nt
	s_add_u32 s100, s100, 0x2000
	s_addc_u32 s101, s101, 0
	global_load_dwordx4 v[18:21], v254, s[100:101] nt
	s_add_u32 s100, s100, 0x2000
	s_addc_u32 s101, s101, 0
	global_load_dwordx4 v[14:17], v254, s[100:101] nt
	s_or_b32 s1, s1, 1
	v_readlane_b32 s4, v71, s1
	s_ashr_i32 s5, s4, 31
	s_lshl_b64 s[4:5], s[4:5], 16
	s_add_i32 s13, s13, -1
	s_waitcnt vmcnt(31)
	v_pk_mul_f32 v[82:83], v[8:9], v[82:83]
	v_pk_mul_f32 v[80:81], v[6:7], v[80:81]
	s_nop 0
	v_pk_mov_b32 v[156:157], v[80:81], v[82:83] op_sel:[1,0]
	v_mov_b32_e32 v81, v83
	v_pk_add_f32 v[80:81], v[156:157], v[80:81]
	s_nop 0
	v_add_f32_e32 v79, v80, v81
	s_waitcnt vmcnt(30)
	v_pk_mul_f32 v[80:81], v[8:9], v[86:87]
	v_pk_mul_f32 v[82:83], v[6:7], v[84:85]
	v_add_f32_dpp v79, v79, v79 quad_perm:[1,0,3,2] row_mask:0xf bank_mask:0xf bound_ctrl:1
	v_pk_mov_b32 v[84:85], v[82:83], v[80:81] op_sel:[1,0]
	v_mov_b32_e32 v83, v81
	v_pk_add_f32 v[80:81], v[84:85], v[82:83]
	v_add_f32_dpp v79, v79, v79 quad_perm:[2,3,0,1] row_mask:0xf bank_mask:0xf bound_ctrl:1
	v_add_f32_e32 v80, v80, v81
	s_nop 1
	v_add_f32_dpp v80, v80, v80 quad_perm:[1,0,3,2] row_mask:0xf bank_mask:0xf bound_ctrl:1
	v_add_f32_dpp v79, v79, v79 row_half_mirror row_mask:0xf bank_mask:0xf bound_ctrl:1
	s_nop 0
	v_add_f32_dpp v80, v80, v80 quad_perm:[2,3,0,1] row_mask:0xf bank_mask:0xf bound_ctrl:1
	v_add_f32_dpp v79, v79, v79 row_mirror row_mask:0xf bank_mask:0xf bound_ctrl:1
	v_mul_f32_e32 v156, 0x3e38aa3b, v79
	v_add_f32_dpp v80, v80, v80 row_half_mirror row_mask:0xf bank_mask:0xf bound_ctrl:1
	s_waitcnt vmcnt(29)
	v_pk_mul_f32 v[82:83], v[6:7], v[88:89]
	v_add_f32_dpp v86, v80, v80 row_mirror row_mask:0xf bank_mask:0xf bound_ctrl:1
	v_mul_f32_e32 v80, 0x3e38aa3b, v86
	v_max3_f32 v87, v156, s42, v80
	v_pk_mul_f32 v[80:81], v[8:9], v[90:91]
	s_nop 0
	v_pk_mov_b32 v[84:85], v[82:83], v[80:81] op_sel:[1,0]
	v_mov_b32_e32 v83, v81
	v_pk_add_f32 v[80:81], v[84:85], v[82:83]
	s_nop 0
	v_add_f32_e32 v80, v80, v81
	s_waitcnt vmcnt(28)
	v_pk_mul_f32 v[82:83], v[6:7], v[92:93]
	v_add_f32_dpp v80, v80, v80 quad_perm:[1,0,3,2] row_mask:0xf bank_mask:0xf bound_ctrl:1
	s_nop 1
	v_add_f32_dpp v80, v80, v80 quad_perm:[2,3,0,1] row_mask:0xf bank_mask:0xf bound_ctrl:1
	s_nop 1
	v_add_f32_dpp v80, v80, v80 row_half_mirror row_mask:0xf bank_mask:0xf bound_ctrl:1
	s_nop 1
	v_add_f32_dpp v88, v80, v80 row_mirror row_mask:0xf bank_mask:0xf bound_ctrl:1
	v_pk_mul_f32 v[80:81], v[8:9], v[94:95]
	v_mul_f32_e32 v89, 0x3e38aa3b, v88
	v_pk_mov_b32 v[84:85], v[82:83], v[80:81] op_sel:[1,0]
	v_mov_b32_e32 v83, v81
	v_pk_add_f32 v[80:81], v[84:85], v[82:83]
	s_waitcnt vmcnt(27)
	v_pk_mul_f32 v[82:83], v[6:7], v[96:97]
	v_add_f32_e32 v80, v80, v81
	s_nop 1
	v_add_f32_dpp v80, v80, v80 quad_perm:[1,0,3,2] row_mask:0xf bank_mask:0xf bound_ctrl:1
	s_nop 1
	v_add_f32_dpp v80, v80, v80 quad_perm:[2,3,0,1] row_mask:0xf bank_mask:0xf bound_ctrl:1
	s_nop 1
	v_add_f32_dpp v80, v80, v80 row_half_mirror row_mask:0xf bank_mask:0xf bound_ctrl:1
	s_nop 1
	v_add_f32_dpp v90, v80, v80 row_mirror row_mask:0xf bank_mask:0xf bound_ctrl:1
	v_mul_f32_e32 v80, 0x3e38aa3b, v90
	v_max3_f32 v87, v87, v89, v80
	v_pk_mul_f32 v[80:81], v[8:9], v[98:99]
	s_nop 0
	v_pk_mov_b32 v[84:85], v[82:83], v[80:81] op_sel:[1,0]
	v_mov_b32_e32 v83, v81
	v_pk_add_f32 v[80:81], v[84:85], v[82:83]
	s_waitcnt vmcnt(26)
	v_pk_mul_f32 v[82:83], v[6:7], v[100:101]
	v_add_f32_e32 v80, v80, v81
	s_nop 1
	v_add_f32_dpp v80, v80, v80 quad_perm:[1,0,3,2] row_mask:0xf bank_mask:0xf bound_ctrl:1
	s_nop 1
	v_add_f32_dpp v80, v80, v80 quad_perm:[2,3,0,1] row_mask:0xf bank_mask:0xf bound_ctrl:1
	s_nop 1
	v_add_f32_dpp v80, v80, v80 row_half_mirror row_mask:0xf bank_mask:0xf bound_ctrl:1
	s_nop 1
	v_add_f32_dpp v89, v80, v80 row_mirror row_mask:0xf bank_mask:0xf bound_ctrl:1
	v_pk_mul_f32 v[80:81], v[8:9], v[102:103]
	v_mul_f32_e32 v91, 0x3e38aa3b, v89
	v_pk_mov_b32 v[84:85], v[82:83], v[80:81] op_sel:[1,0]
	v_mov_b32_e32 v83, v81
	v_pk_add_f32 v[80:81], v[84:85], v[82:83]
	s_waitcnt vmcnt(25)
	v_pk_mul_f32 v[82:83], v[6:7], v[104:105]
	v_add_f32_e32 v80, v80, v81
	s_nop 1
	v_add_f32_dpp v80, v80, v80 quad_perm:[1,0,3,2] row_mask:0xf bank_mask:0xf bound_ctrl:1
	s_nop 1
	v_add_f32_dpp v80, v80, v80 quad_perm:[2,3,0,1] row_mask:0xf bank_mask:0xf bound_ctrl:1
	s_nop 1
	v_add_f32_dpp v80, v80, v80 row_half_mirror row_mask:0xf bank_mask:0xf bound_ctrl:1
	s_nop 1
	v_add_f32_dpp v92, v80, v80 row_mirror row_mask:0xf bank_mask:0xf bound_ctrl:1
	v_mul_f32_e32 v80, 0x3e38aa3b, v92
	v_max3_f32 v87, v87, v91, v80
	v_pk_mul_f32 v[80:81], v[8:9], v[106:107]
	s_nop 0
	v_pk_mov_b32 v[84:85], v[82:83], v[80:81] op_sel:[1,0]
	v_mov_b32_e32 v83, v81
	v_pk_add_f32 v[80:81], v[84:85], v[82:83]
	s_waitcnt vmcnt(24)
	v_pk_mul_f32 v[82:83], v[6:7], v[108:109]
	v_add_f32_e32 v80, v80, v81
	s_nop 1
	v_add_f32_dpp v80, v80, v80 quad_perm:[1,0,3,2] row_mask:0xf bank_mask:0xf bound_ctrl:1
	s_nop 1
	v_add_f32_dpp v80, v80, v80 quad_perm:[2,3,0,1] row_mask:0xf bank_mask:0xf bound_ctrl:1
	s_nop 1
	v_add_f32_dpp v80, v80, v80 row_half_mirror row_mask:0xf bank_mask:0xf bound_ctrl:1
	s_nop 1
	v_add_f32_dpp v91, v80, v80 row_mirror row_mask:0xf bank_mask:0xf bound_ctrl:1
	v_pk_mul_f32 v[80:81], v[8:9], v[110:111]
	v_mul_f32_e32 v93, 0x3e38aa3b, v91
	v_pk_mov_b32 v[84:85], v[82:83], v[80:81] op_sel:[1,0]
	v_mov_b32_e32 v83, v81
	v_pk_add_f32 v[80:81], v[84:85], v[82:83]
	s_waitcnt vmcnt(23)
	v_pk_mul_f32 v[82:83], v[6:7], v[112:113]
	v_add_f32_e32 v80, v80, v81
	s_nop 1
	v_add_f32_dpp v80, v80, v80 quad_perm:[1,0,3,2] row_mask:0xf bank_mask:0xf bound_ctrl:1
	s_nop 1
	v_add_f32_dpp v80, v80, v80 quad_perm:[2,3,0,1] row_mask:0xf bank_mask:0xf bound_ctrl:1
	s_nop 1
	v_add_f32_dpp v80, v80, v80 row_half_mirror row_mask:0xf bank_mask:0xf bound_ctrl:1
	s_nop 1
	v_add_f32_dpp v94, v80, v80 row_mirror row_mask:0xf bank_mask:0xf bound_ctrl:1
	v_mul_f32_e32 v80, 0x3e38aa3b, v94
	v_max3_f32 v87, v87, v93, v80
	v_pk_mul_f32 v[80:81], v[8:9], v[114:115]
	s_nop 0
	v_pk_mov_b32 v[84:85], v[82:83], v[80:81] op_sel:[1,0]
	v_mov_b32_e32 v83, v81
	v_pk_add_f32 v[80:81], v[84:85], v[82:83]
	s_waitcnt vmcnt(22)
	v_pk_mul_f32 v[82:83], v[6:7], v[116:117]
	v_add_f32_e32 v80, v80, v81
	s_nop 1
	v_add_f32_dpp v80, v80, v80 quad_perm:[1,0,3,2] row_mask:0xf bank_mask:0xf bound_ctrl:1
	s_nop 1
	v_add_f32_dpp v80, v80, v80 quad_perm:[2,3,0,1] row_mask:0xf bank_mask:0xf bound_ctrl:1
	s_nop 1
	v_add_f32_dpp v80, v80, v80 row_half_mirror row_mask:0xf bank_mask:0xf bound_ctrl:1
	s_nop 1
	v_add_f32_dpp v93, v80, v80 row_mirror row_mask:0xf bank_mask:0xf bound_ctrl:1
	v_pk_mul_f32 v[80:81], v[8:9], v[118:119]
	v_mul_f32_e32 v95, 0x3e38aa3b, v93
	v_pk_mov_b32 v[84:85], v[82:83], v[80:81] op_sel:[1,0]
	v_mov_b32_e32 v83, v81
	v_pk_add_f32 v[80:81], v[84:85], v[82:83]
	s_waitcnt vmcnt(21)
	v_pk_mul_f32 v[82:83], v[6:7], v[120:121]
	v_add_f32_e32 v80, v80, v81
	s_nop 1
	v_add_f32_dpp v80, v80, v80 quad_perm:[1,0,3,2] row_mask:0xf bank_mask:0xf bound_ctrl:1
	s_nop 1
	v_add_f32_dpp v80, v80, v80 quad_perm:[2,3,0,1] row_mask:0xf bank_mask:0xf bound_ctrl:1
	s_nop 1
	v_add_f32_dpp v80, v80, v80 row_half_mirror row_mask:0xf bank_mask:0xf bound_ctrl:1
	s_nop 1
	v_add_f32_dpp v96, v80, v80 row_mirror row_mask:0xf bank_mask:0xf bound_ctrl:1
	v_mul_f32_e32 v80, 0x3e38aa3b, v96
	v_max3_f32 v87, v87, v95, v80
	v_pk_mul_f32 v[80:81], v[8:9], v[122:123]
	s_nop 0
	v_pk_mov_b32 v[84:85], v[82:83], v[80:81] op_sel:[1,0]
	v_mov_b32_e32 v83, v81
	v_pk_add_f32 v[80:81], v[84:85], v[82:83]
	s_waitcnt vmcnt(20)
	v_pk_mul_f32 v[82:83], v[6:7], v[124:125]
	v_add_f32_e32 v80, v80, v81
	s_nop 1
	v_add_f32_dpp v80, v80, v80 quad_perm:[1,0,3,2] row_mask:0xf bank_mask:0xf bound_ctrl:1
	s_nop 1
	v_add_f32_dpp v80, v80, v80 quad_perm:[2,3,0,1] row_mask:0xf bank_mask:0xf bound_ctrl:1
	s_nop 1
	v_add_f32_dpp v80, v80, v80 row_half_mirror row_mask:0xf bank_mask:0xf bound_ctrl:1
	s_nop 1
	v_add_f32_dpp v95, v80, v80 row_mirror row_mask:0xf bank_mask:0xf bound_ctrl:1
	v_pk_mul_f32 v[80:81], v[8:9], v[126:127]
	v_mul_f32_e32 v97, 0x3e38aa3b, v95
	v_pk_mov_b32 v[84:85], v[82:83], v[80:81] op_sel:[1,0]
	v_mov_b32_e32 v83, v81
	v_pk_add_f32 v[80:81], v[84:85], v[82:83]
	s_waitcnt vmcnt(19)
	v_pk_mul_f32 v[82:83], v[6:7], v[128:129]
	v_add_f32_e32 v80, v80, v81
	s_nop 1
	v_add_f32_dpp v80, v80, v80 quad_perm:[1,0,3,2] row_mask:0xf bank_mask:0xf bound_ctrl:1
	s_nop 1
	v_add_f32_dpp v80, v80, v80 quad_perm:[2,3,0,1] row_mask:0xf bank_mask:0xf bound_ctrl:1
	s_nop 1
	v_add_f32_dpp v80, v80, v80 row_half_mirror row_mask:0xf bank_mask:0xf bound_ctrl:1
	s_nop 1
	v_add_f32_dpp v98, v80, v80 row_mirror row_mask:0xf bank_mask:0xf bound_ctrl:1
	v_mul_f32_e32 v80, 0x3e38aa3b, v98
	v_max3_f32 v87, v87, v97, v80
	v_pk_mul_f32 v[80:81], v[8:9], v[130:131]
	s_nop 0
	v_pk_mov_b32 v[84:85], v[82:83], v[80:81] op_sel:[1,0]
	v_mov_b32_e32 v83, v81
	v_pk_add_f32 v[80:81], v[84:85], v[82:83]
	s_waitcnt vmcnt(18)
	v_pk_mul_f32 v[82:83], v[6:7], v[132:133]
	v_add_f32_e32 v80, v80, v81
	s_nop 1
	v_add_f32_dpp v80, v80, v80 quad_perm:[1,0,3,2] row_mask:0xf bank_mask:0xf bound_ctrl:1
	s_nop 1
	v_add_f32_dpp v80, v80, v80 quad_perm:[2,3,0,1] row_mask:0xf bank_mask:0xf bound_ctrl:1
	s_nop 1
	v_add_f32_dpp v80, v80, v80 row_half_mirror row_mask:0xf bank_mask:0xf bound_ctrl:1
	s_nop 1
	v_add_f32_dpp v97, v80, v80 row_mirror row_mask:0xf bank_mask:0xf bound_ctrl:1
	v_pk_mul_f32 v[80:81], v[8:9], v[134:135]
	v_mul_f32_e32 v99, 0x3e38aa3b, v97
	v_pk_mov_b32 v[84:85], v[82:83], v[80:81] op_sel:[1,0]
	v_mov_b32_e32 v83, v81
	v_pk_add_f32 v[80:81], v[84:85], v[82:83]
	s_waitcnt vmcnt(17)
	v_pk_mul_f32 v[82:83], v[6:7], v[136:137]
	v_add_f32_e32 v80, v80, v81
	s_nop 1
	v_add_f32_dpp v80, v80, v80 quad_perm:[1,0,3,2] row_mask:0xf bank_mask:0xf bound_ctrl:1
	s_nop 1
	v_add_f32_dpp v80, v80, v80 quad_perm:[2,3,0,1] row_mask:0xf bank_mask:0xf bound_ctrl:1
	s_nop 1
	v_add_f32_dpp v80, v80, v80 row_half_mirror row_mask:0xf bank_mask:0xf bound_ctrl:1
	s_nop 1
	v_add_f32_dpp v100, v80, v80 row_mirror row_mask:0xf bank_mask:0xf bound_ctrl:1
	v_mul_f32_e32 v80, 0x3e38aa3b, v100
	v_max3_f32 v87, v87, v99, v80
	v_pk_mul_f32 v[80:81], v[8:9], v[138:139]
	s_nop 0
	v_pk_mov_b32 v[84:85], v[82:83], v[80:81] op_sel:[1,0]
	v_mov_b32_e32 v83, v81
	v_pk_add_f32 v[80:81], v[84:85], v[82:83]
	s_waitcnt vmcnt(16)
	v_pk_mul_f32 v[82:83], v[6:7], v[140:141]
	v_add_f32_e32 v80, v80, v81
	s_nop 1
	v_add_f32_dpp v80, v80, v80 quad_perm:[1,0,3,2] row_mask:0xf bank_mask:0xf bound_ctrl:1
	s_nop 1
	v_add_f32_dpp v80, v80, v80 quad_perm:[2,3,0,1] row_mask:0xf bank_mask:0xf bound_ctrl:1
	s_nop 1
	v_add_f32_dpp v80, v80, v80 row_half_mirror row_mask:0xf bank_mask:0xf bound_ctrl:1
	s_nop 1
	v_add_f32_dpp v99, v80, v80 row_mirror row_mask:0xf bank_mask:0xf bound_ctrl:1
	v_pk_mul_f32 v[80:81], v[8:9], v[142:143]
	v_mul_f32_e32 v101, 0x3e38aa3b, v99
	v_pk_mov_b32 v[84:85], v[82:83], v[80:81] op_sel:[1,0]
	v_mov_b32_e32 v83, v81
	v_pk_add_f32 v[80:81], v[84:85], v[82:83]
	s_nop 0
	v_add_f32_e32 v80, v80, v81
	s_nop 1
	v_add_f32_dpp v80, v80, v80 quad_perm:[1,0,3,2] row_mask:0xf bank_mask:0xf bound_ctrl:1
	s_nop 1
	v_add_f32_dpp v80, v80, v80 quad_perm:[2,3,0,1] row_mask:0xf bank_mask:0xf bound_ctrl:1
	s_nop 1
	v_add_f32_dpp v80, v80, v80 row_half_mirror row_mask:0xf bank_mask:0xf bound_ctrl:1
	s_nop 1
	v_add_f32_dpp v84, v80, v80 row_mirror row_mask:0xf bank_mask:0xf bound_ctrl:1
	v_mul_f32_e32 v80, 0x3e38aa3b, v84
	v_max3_f32 v80, v87, v101, v80
	v_mov_b32_e32 v81, v80
	s_nop 1
	v_permlane16_swap_b32_e32 v80, v81
	v_max_f32_e32 v81, v81, v81
	v_max_f32_e32 v80, v80, v80
	v_max_f32_e32 v80, v80, v81
	v_mov_b32_e32 v81, v80
	s_nop 1
	v_permlane32_swap_b32_e32 v80, v81
	v_max3_f32 v156, v78, v80, v81
	v_fma_f32 v79, v79, s41, -v156
	v_sub_f32_e32 v78, v78, v156
	v_exp_f32_e32 v80, v79
	v_exp_f32_e32 v78, v78
	v_mov_b32_e32 v79, v80
	v_fmac_f32_e32 v79, v69, v78
	s_waitcnt vmcnt(15)
	v_pk_mul_f32 v[82:83], v[146:147], v[80:81] op_sel_hi:[1,0]
	v_pk_mul_f32 v[80:81], v[144:145], v[80:81] op_sel_hi:[1,0]
	v_fma_f32 v69, v86, s41, -v156
	v_pk_fma_f32 v[72:73], v[72:73], v[78:79], v[80:81] op_sel_hi:[1,0,1]
	v_pk_fma_f32 v[74:75], v[74:75], v[78:79], v[82:83] op_sel_hi:[1,0,1]
	v_exp_f32_e32 v78, v69
	s_nop 0
	v_add_f32_e32 v69, v78, v79
	s_waitcnt vmcnt(14)
	v_pk_fma_f32 v[74:75], v[150:151], v[78:79], v[74:75] op_sel_hi:[1,0,1]
	v_pk_fma_f32 v[72:73], v[148:149], v[78:79], v[72:73] op_sel_hi:[1,0,1]
	v_fma_f32 v78, v88, s41, -v156
	v_exp_f32_e32 v78, v78
	s_nop 0
	v_add_f32_e32 v69, v78, v69
	s_waitcnt vmcnt(13)
	v_pk_fma_f32 v[72:73], v[152:153], v[78:79], v[72:73] op_sel_hi:[1,0,1]
	v_pk_fma_f32 v[74:75], v[154:155], v[78:79], v[74:75] op_sel_hi:[1,0,1]
	v_fma_f32 v78, v90, s41, -v156
	v_exp_f32_e32 v78, v78
	s_waitcnt vmcnt(12)
	v_pk_fma_f32 v[62:63], v[62:63], v[78:79], v[72:73] op_sel_hi:[1,0,1]
	v_fma_f32 v72, v89, s41, -v156
	v_exp_f32_e32 v72, v72
	v_add_f32_e32 v69, v78, v69
	v_pk_fma_f32 v[64:65], v[64:65], v[78:79], v[74:75] op_sel_hi:[1,0,1]
	s_lshl_b64 s[98:99], s[6:7], 2
	s_add_u32 s98, s98, s84
	s_addc_u32 s99, s99, s85
	s_add_u32 s98, s98, 0x20000
	s_addc_u32 s99, s99, 0
	global_load_dwordx4 v[78:81], v254, s[98:99] nt
	s_waitcnt vmcnt(12)
	v_pk_fma_f32 v[58:59], v[58:59], v[72:73], v[62:63] op_sel_hi:[1,0,1]
	v_fma_f32 v62, v92, s41, -v156
	v_exp_f32_e32 v62, v62
	v_add_f32_e32 v69, v72, v69
	v_pk_fma_f32 v[60:61], v[60:61], v[72:73], v[64:65] op_sel_hi:[1,0,1]
	v_add_f32_e32 v63, v62, v69
	s_waitcnt vmcnt(11)
	v_pk_fma_f32 v[54:55], v[54:55], v[62:63], v[58:59] op_sel_hi:[1,0,1]
	v_fma_f32 v58, v91, s41, -v156
	v_exp_f32_e32 v58, v58
	v_pk_fma_f32 v[56:57], v[56:57], v[62:63], v[60:61] op_sel_hi:[1,0,1]
	v_add_f32_e32 v59, v58, v63
	s_waitcnt vmcnt(10)
	v_pk_fma_f32 v[50:51], v[50:51], v[58:59], v[54:55] op_sel_hi:[1,0,1]
	v_fma_f32 v54, v94, s41, -v156
	v_exp_f32_e32 v54, v54
	v_pk_fma_f32 v[52:53], v[52:53], v[58:59], v[56:57] op_sel_hi:[1,0,1]
	v_add_f32_e32 v55, v54, v59
	s_waitcnt vmcnt(9)
	v_pk_fma_f32 v[46:47], v[46:47], v[54:55], v[50:51] op_sel_hi:[1,0,1]
	v_fma_f32 v50, v93, s41, -v156
	v_exp_f32_e32 v50, v50
	v_pk_fma_f32 v[48:49], v[48:49], v[54:55], v[52:53] op_sel_hi:[1,0,1]
	v_add_f32_e32 v51, v50, v55
	s_waitcnt vmcnt(8)
	v_pk_fma_f32 v[42:43], v[42:43], v[50:51], v[46:47] op_sel_hi:[1,0,1]
	v_fma_f32 v46, v96, s41, -v156
	v_exp_f32_e32 v46, v46
	v_pk_fma_f32 v[44:45], v[44:45], v[50:51], v[48:49] op_sel_hi:[1,0,1]
	v_add_f32_e32 v47, v46, v51
	s_waitcnt vmcnt(7)
	v_pk_fma_f32 v[38:39], v[38:39], v[46:47], v[42:43] op_sel_hi:[1,0,1]
	v_fma_f32 v42, v95, s41, -v156
	v_exp_f32_e32 v42, v42
	v_pk_fma_f32 v[40:41], v[40:41], v[46:47], v[44:45] op_sel_hi:[1,0,1]
	v_add_f32_e32 v43, v42, v47
	s_waitcnt vmcnt(6)
	v_pk_fma_f32 v[34:35], v[34:35], v[42:43], v[38:39] op_sel_hi:[1,0,1]
	v_fma_f32 v38, v98, s41, -v156
	v_exp_f32_e32 v38, v38
	v_pk_fma_f32 v[36:37], v[36:37], v[42:43], v[40:41] op_sel_hi:[1,0,1]
	v_add_f32_e32 v39, v38, v43
	s_waitcnt vmcnt(5)
	v_pk_fma_f32 v[30:31], v[30:31], v[38:39], v[34:35] op_sel_hi:[1,0,1]
	v_fma_f32 v34, v97, s41, -v156
	v_exp_f32_e32 v34, v34
	v_pk_fma_f32 v[32:33], v[32:33], v[38:39], v[36:37] op_sel_hi:[1,0,1]
	v_add_f32_e32 v35, v34, v39
	s_waitcnt vmcnt(4)
	v_pk_fma_f32 v[26:27], v[26:27], v[34:35], v[30:31] op_sel_hi:[1,0,1]
	v_fma_f32 v30, v100, s41, -v156
	v_exp_f32_e32 v30, v30
	v_pk_fma_f32 v[28:29], v[28:29], v[34:35], v[32:33] op_sel_hi:[1,0,1]
	v_add_f32_e32 v31, v30, v35
	s_waitcnt vmcnt(3)
	v_pk_fma_f32 v[22:23], v[22:23], v[30:31], v[26:27] op_sel_hi:[1,0,1]
	v_fma_f32 v26, v99, s41, -v156
	v_exp_f32_e32 v26, v26
	v_pk_fma_f32 v[24:25], v[24:25], v[30:31], v[28:29] op_sel_hi:[1,0,1]
	v_add_f32_e32 v27, v26, v31
	s_waitcnt vmcnt(2)
	v_pk_fma_f32 v[18:19], v[18:19], v[26:27], v[22:23] op_sel_hi:[1,0,1]
	v_fma_f32 v22, v84, s41, -v156
	s_add_u32 s98, s98, 0x2000
	s_addc_u32 s99, s99, 0
	global_load_dwordx4 v[82:85], v254, s[98:99] nt
	s_add_u32 s98, s98, 0x2000
	s_addc_u32 s99, s99, 0
	global_load_dwordx4 v[86:89], v254, s[98:99] nt
	s_add_u32 s98, s98, 0x2000
	s_addc_u32 s99, s99, 0
	global_load_dwordx4 v[90:93], v254, s[98:99] nt
	s_add_u32 s98, s98, 0x2000
	s_addc_u32 s99, s99, 0
	global_load_dwordx4 v[94:97], v254, s[98:99] nt
	s_add_u32 s98, s98, 0x2000
	s_addc_u32 s99, s99, 0
	global_load_dwordx4 v[98:101], v254, s[98:99] nt
	s_add_u32 s98, s98, 0x2000
	s_addc_u32 s99, s99, 0
	global_load_dwordx4 v[102:105], v254, s[98:99] nt
	s_add_u32 s98, s98, 0x2000
	s_addc_u32 s99, s99, 0
	global_load_dwordx4 v[106:109], v254, s[98:99] nt
	s_add_u32 s98, s98, 0x2000
	s_addc_u32 s99, s99, 0
	global_load_dwordx4 v[110:113], v254, s[98:99] nt
	s_add_u32 s98, s98, 0x2000
	s_addc_u32 s99, s99, 0
	global_load_dwordx4 v[114:117], v254, s[98:99] nt
	s_add_u32 s98, s98, 0x2000
	s_addc_u32 s99, s99, 0
	global_load_dwordx4 v[118:121], v254, s[98:99] nt
	s_add_u32 s98, s98, 0x2000
	s_addc_u32 s99, s99, 0
	global_load_dwordx4 v[122:125], v254, s[98:99] nt
	s_add_u32 s98, s98, 0x2000
	s_addc_u32 s99, s99, 0
	global_load_dwordx4 v[126:129], v254, s[98:99] nt
	s_add_u32 s98, s98, 0x2000
	s_addc_u32 s99, s99, 0
	global_load_dwordx4 v[130:133], v254, s[98:99] nt
	s_add_u32 s98, s98, 0x2000
	s_addc_u32 s99, s99, 0
	global_load_dwordx4 v[134:137], v254, s[98:99] nt
	s_add_u32 s98, s98, 0x2000
	s_addc_u32 s99, s99, 0
	global_load_dwordx4 v[138:141], v254, s[98:99] nt
	s_lshl_b64 s[100:101], s[6:7], 2
	s_add_u32 s100, s100, s86
	s_addc_u32 s101, s101, s87
	s_add_u32 s100, s100, 0x20000
	s_addc_u32 s101, s101, 0
	global_load_dwordx4 v[142:145], v254, s[100:101] nt
	s_add_u32 s100, s100, 0x2000
	s_addc_u32 s101, s101, 0
	global_load_dwordx4 v[146:149], v254, s[100:101] nt
	s_add_u32 s100, s100, 0x2000
	s_addc_u32 s101, s101, 0
	global_load_dwordx4 v[150:153], v254, s[100:101] nt
	s_add_u32 s100, s100, 0x2000
	s_addc_u32 s101, s101, 0
	global_load_dwordx4 v[62:65], v254, s[100:101] nt
	s_add_u32 s100, s100, 0x2000
	s_addc_u32 s101, s101, 0
	global_load_dwordx4 v[58:61], v254, s[100:101] nt
	s_add_u32 s100, s100, 0x2000
	s_addc_u32 s101, s101, 0
	global_load_dwordx4 v[54:57], v254, s[100:101] nt
	s_add_u32 s100, s100, 0x2000
	s_addc_u32 s101, s101, 0
	global_load_dwordx4 v[50:53], v254, s[100:101] nt
	s_add_u32 s100, s100, 0x2000
	s_addc_u32 s101, s101, 0
	global_load_dwordx4 v[46:49], v254, s[100:101] nt
	s_add_u32 s100, s100, 0x2000
	s_addc_u32 s101, s101, 0
	global_load_dwordx4 v[42:45], v254, s[100:101] nt
	s_add_u32 s100, s100, 0x2000
	s_addc_u32 s101, s101, 0
	global_load_dwordx4 v[38:41], v254, s[100:101] nt
	s_add_u32 s100, s100, 0x2000
	s_addc_u32 s101, s101, 0
	global_load_dwordx4 v[34:37], v254, s[100:101] nt
	s_add_u32 s100, s100, 0x2000
	s_addc_u32 s101, s101, 0
	global_load_dwordx4 v[30:33], v254, s[100:101] nt
	v_exp_f32_e32 v22, v22
	v_pk_fma_f32 v[20:21], v[20:21], v[26:27], v[24:25] op_sel_hi:[1,0,1]
	s_waitcnt vmcnt(28)
	v_pk_fma_f32 v[74:75], v[14:15], v[22:23], v[18:19] op_sel_hi:[1,0,1]
	v_pk_fma_f32 v[72:73], v[16:17], v[22:23], v[20:21] op_sel_hi:[1,0,1]
	v_add_f32_e32 v69, v22, v27
	s_add_u32 s100, s100, 0x2000
	s_addc_u32 s101, s101, 0
	global_load_dwordx4 v[26:29], v254, s[100:101] nt
	s_add_u32 s100, s100, 0x2000
	s_addc_u32 s101, s101, 0
	global_load_dwordx4 v[22:25], v254, s[100:101] nt
	s_add_u32 s100, s100, 0x2000
	s_addc_u32 s101, s101, 0
	global_load_dwordx4 v[18:21], v254, s[100:101] nt
	s_add_u32 s100, s100, 0x2000
	s_addc_u32 s101, s101, 0
	global_load_dwordx4 v[14:17], v254, s[100:101] nt
	s_waitcnt vmcnt(31)
	v_pk_mul_f32 v[80:81], v[8:9], v[80:81]
	v_pk_mul_f32 v[78:79], v[6:7], v[78:79]
	s_nop 0
	v_pk_mov_b32 v[154:155], v[78:79], v[80:81] op_sel:[1,0]
	v_mov_b32_e32 v79, v81
	v_pk_add_f32 v[78:79], v[154:155], v[78:79]
	s_nop 0
	v_add_f32_e32 v78, v78, v79
	s_nop 1
	v_add_f32_dpp v78, v78, v78 quad_perm:[1,0,3,2] row_mask:0xf bank_mask:0xf bound_ctrl:1
	s_nop 1
	v_add_f32_dpp v78, v78, v78 quad_perm:[2,3,0,1] row_mask:0xf bank_mask:0xf bound_ctrl:1
	s_nop 1
	v_add_f32_dpp v78, v78, v78 row_half_mirror row_mask:0xf bank_mask:0xf bound_ctrl:1
	s_waitcnt vmcnt(30)
	v_pk_mul_f32 v[80:81], v[6:7], v[82:83]
	v_add_f32_dpp v154, v78, v78 row_mirror row_mask:0xf bank_mask:0xf bound_ctrl:1
	v_pk_mul_f32 v[78:79], v[8:9], v[84:85]
	s_nop 0
	v_pk_mov_b32 v[82:83], v[80:81], v[78:79] op_sel:[1,0]
	v_mov_b32_e32 v81, v79
	v_pk_add_f32 v[78:79], v[82:83], v[80:81]
	s_nop 0
	v_add_f32_e32 v78, v78, v79
	v_mul_f32_e32 v155, 0x3e38aa3b, v154
	s_nop 0
	v_add_f32_dpp v78, v78, v78 quad_perm:[1,0,3,2] row_mask:0xf bank_mask:0xf bound_ctrl:1
	s_waitcnt vmcnt(29)
	v_pk_mul_f32 v[80:81], v[6:7], v[86:87]
	v_add_f32_dpp v78, v78, v78 quad_perm:[2,3,0,1] row_mask:0xf bank_mask:0xf bound_ctrl:1
	s_nop 1
	v_add_f32_dpp v78, v78, v78 row_half_mirror row_mask:0xf bank_mask:0xf bound_ctrl:1
	s_nop 1
	v_add_f32_dpp v84, v78, v78 row_mirror row_mask:0xf bank_mask:0xf bound_ctrl:1
	v_mul_f32_e32 v78, 0x3e38aa3b, v84
	v_max3_f32 v85, v155, s42, v78
	v_pk_mul_f32 v[78:79], v[8:9], v[88:89]
	s_nop 0
	v_pk_mov_b32 v[82:83], v[80:81], v[78:79] op_sel:[1,0]
	v_mov_b32_e32 v81, v79
	v_pk_add_f32 v[78:79], v[82:83], v[80:81]
	s_waitcnt vmcnt(28)
	v_pk_mul_f32 v[80:81], v[6:7], v[90:91]
	v_add_f32_e32 v78, v78, v79
	s_nop 1
	v_add_f32_dpp v78, v78, v78 quad_perm:[1,0,3,2] row_mask:0xf bank_mask:0xf bound_ctrl:1
	s_nop 1
	v_add_f32_dpp v78, v78, v78 quad_perm:[2,3,0,1] row_mask:0xf bank_mask:0xf bound_ctrl:1
	s_nop 1
	v_add_f32_dpp v78, v78, v78 row_half_mirror row_mask:0xf bank_mask:0xf bound_ctrl:1
	s_nop 1
	v_add_f32_dpp v86, v78, v78 row_mirror row_mask:0xf bank_mask:0xf bound_ctrl:1
	v_pk_mul_f32 v[78:79], v[8:9], v[92:93]
	v_mul_f32_e32 v87, 0x3e38aa3b, v86
	v_pk_mov_b32 v[82:83], v[80:81], v[78:79] op_sel:[1,0]
	v_mov_b32_e32 v81, v79
	v_pk_add_f32 v[78:79], v[82:83], v[80:81]
	s_waitcnt vmcnt(27)
	v_pk_mul_f32 v[80:81], v[6:7], v[94:95]
	v_add_f32_e32 v78, v78, v79
	s_nop 1
	v_add_f32_dpp v78, v78, v78 quad_perm:[1,0,3,2] row_mask:0xf bank_mask:0xf bound_ctrl:1
	s_nop 1
	v_add_f32_dpp v78, v78, v78 quad_perm:[2,3,0,1] row_mask:0xf bank_mask:0xf bound_ctrl:1
	s_nop 1
	v_add_f32_dpp v78, v78, v78 row_half_mirror row_mask:0xf bank_mask:0xf bound_ctrl:1
	s_nop 1
	v_add_f32_dpp v88, v78, v78 row_mirror row_mask:0xf bank_mask:0xf bound_ctrl:1
	v_mul_f32_e32 v78, 0x3e38aa3b, v88
	v_max3_f32 v85, v85, v87, v78
	v_pk_mul_f32 v[78:79], v[8:9], v[96:97]
	s_nop 0
	v_pk_mov_b32 v[82:83], v[80:81], v[78:79] op_sel:[1,0]
	v_mov_b32_e32 v81, v79
	v_pk_add_f32 v[78:79], v[82:83], v[80:81]
	s_waitcnt vmcnt(26)
	v_pk_mul_f32 v[80:81], v[6:7], v[98:99]
	v_add_f32_e32 v78, v78, v79
	s_nop 1
	v_add_f32_dpp v78, v78, v78 quad_perm:[1,0,3,2] row_mask:0xf bank_mask:0xf bound_ctrl:1
	s_nop 1
	v_add_f32_dpp v78, v78, v78 quad_perm:[2,3,0,1] row_mask:0xf bank_mask:0xf bound_ctrl:1
	s_nop 1
	v_add_f32_dpp v78, v78, v78 row_half_mirror row_mask:0xf bank_mask:0xf bound_ctrl:1
	s_nop 1
	v_add_f32_dpp v87, v78, v78 row_mirror row_mask:0xf bank_mask:0xf bound_ctrl:1
	v_pk_mul_f32 v[78:79], v[8:9], v[100:101]
	v_mul_f32_e32 v89, 0x3e38aa3b, v87
	v_pk_mov_b32 v[82:83], v[80:81], v[78:79] op_sel:[1,0]
	v_mov_b32_e32 v81, v79
	v_pk_add_f32 v[78:79], v[82:83], v[80:81]
	s_waitcnt vmcnt(25)
	v_pk_mul_f32 v[80:81], v[6:7], v[102:103]
	v_add_f32_e32 v78, v78, v79
	s_nop 1
	v_add_f32_dpp v78, v78, v78 quad_perm:[1,0,3,2] row_mask:0xf bank_mask:0xf bound_ctrl:1
	s_nop 1
	v_add_f32_dpp v78, v78, v78 quad_perm:[2,3,0,1] row_mask:0xf bank_mask:0xf bound_ctrl:1
	s_nop 1
	v_add_f32_dpp v78, v78, v78 row_half_mirror row_mask:0xf bank_mask:0xf bound_ctrl:1
	s_nop 1
	v_add_f32_dpp v90, v78, v78 row_mirror row_mask:0xf bank_mask:0xf bound_ctrl:1
	v_mul_f32_e32 v78, 0x3e38aa3b, v90
	v_max3_f32 v85, v85, v89, v78
	v_pk_mul_f32 v[78:79], v[8:9], v[104:105]
	s_nop 0
	v_pk_mov_b32 v[82:83], v[80:81], v[78:79] op_sel:[1,0]
	v_mov_b32_e32 v81, v79
	v_pk_add_f32 v[78:79], v[82:83], v[80:81]
	s_waitcnt vmcnt(24)
	v_pk_mul_f32 v[80:81], v[6:7], v[106:107]
	v_add_f32_e32 v78, v78, v79
	s_nop 1
	v_add_f32_dpp v78, v78, v78 quad_perm:[1,0,3,2] row_mask:0xf bank_mask:0xf bound_ctrl:1
	s_nop 1
	v_add_f32_dpp v78, v78, v78 quad_perm:[2,3,0,1] row_mask:0xf bank_mask:0xf bound_ctrl:1
	s_nop 1
	v_add_f32_dpp v78, v78, v78 row_half_mirror row_mask:0xf bank_mask:0xf bound_ctrl:1
	s_nop 1
	v_add_f32_dpp v89, v78, v78 row_mirror row_mask:0xf bank_mask:0xf bound_ctrl:1
	v_pk_mul_f32 v[78:79], v[8:9], v[108:109]
	v_mul_f32_e32 v91, 0x3e38aa3b, v89
	v_pk_mov_b32 v[82:83], v[80:81], v[78:79] op_sel:[1,0]
	v_mov_b32_e32 v81, v79
	v_pk_add_f32 v[78:79], v[82:83], v[80:81]
	s_waitcnt vmcnt(23)
	v_pk_mul_f32 v[80:81], v[6:7], v[110:111]
	v_add_f32_e32 v78, v78, v79
	s_nop 1
	v_add_f32_dpp v78, v78, v78 quad_perm:[1,0,3,2] row_mask:0xf bank_mask:0xf bound_ctrl:1
	s_nop 1
	v_add_f32_dpp v78, v78, v78 quad_perm:[2,3,0,1] row_mask:0xf bank_mask:0xf bound_ctrl:1
	s_nop 1
	v_add_f32_dpp v78, v78, v78 row_half_mirror row_mask:0xf bank_mask:0xf bound_ctrl:1
	s_nop 1
	v_add_f32_dpp v92, v78, v78 row_mirror row_mask:0xf bank_mask:0xf bound_ctrl:1
	v_mul_f32_e32 v78, 0x3e38aa3b, v92
	v_max3_f32 v85, v85, v91, v78
	v_pk_mul_f32 v[78:79], v[8:9], v[112:113]
	s_nop 0
	v_pk_mov_b32 v[82:83], v[80:81], v[78:79] op_sel:[1,0]
	v_mov_b32_e32 v81, v79
	v_pk_add_f32 v[78:79], v[82:83], v[80:81]
	s_waitcnt vmcnt(22)
	v_pk_mul_f32 v[80:81], v[6:7], v[114:115]
	v_add_f32_e32 v78, v78, v79
	s_nop 1
	v_add_f32_dpp v78, v78, v78 quad_perm:[1,0,3,2] row_mask:0xf bank_mask:0xf bound_ctrl:1
	s_nop 1
	v_add_f32_dpp v78, v78, v78 quad_perm:[2,3,0,1] row_mask:0xf bank_mask:0xf bound_ctrl:1
	s_nop 1
	v_add_f32_dpp v78, v78, v78 row_half_mirror row_mask:0xf bank_mask:0xf bound_ctrl:1
	s_nop 1
	v_add_f32_dpp v91, v78, v78 row_mirror row_mask:0xf bank_mask:0xf bound_ctrl:1
	v_pk_mul_f32 v[78:79], v[8:9], v[116:117]
	v_mul_f32_e32 v93, 0x3e38aa3b, v91
	v_pk_mov_b32 v[82:83], v[80:81], v[78:79] op_sel:[1,0]
	v_mov_b32_e32 v81, v79
	v_pk_add_f32 v[78:79], v[82:83], v[80:81]
	s_waitcnt vmcnt(21)
	v_pk_mul_f32 v[80:81], v[6:7], v[118:119]
	v_add_f32_e32 v78, v78, v79
	s_nop 1
	v_add_f32_dpp v78, v78, v78 quad_perm:[1,0,3,2] row_mask:0xf bank_mask:0xf bound_ctrl:1
	s_nop 1
	v_add_f32_dpp v78, v78, v78 quad_perm:[2,3,0,1] row_mask:0xf bank_mask:0xf bound_ctrl:1
	s_nop 1
	v_add_f32_dpp v78, v78, v78 row_half_mirror row_mask:0xf bank_mask:0xf bound_ctrl:1
	s_nop 1
	v_add_f32_dpp v94, v78, v78 row_mirror row_mask:0xf bank_mask:0xf bound_ctrl:1
	v_mul_f32_e32 v78, 0x3e38aa3b, v94
	v_max3_f32 v85, v85, v93, v78
	v_pk_mul_f32 v[78:79], v[8:9], v[120:121]
	s_nop 0
	v_pk_mov_b32 v[82:83], v[80:81], v[78:79] op_sel:[1,0]
	v_mov_b32_e32 v81, v79
	v_pk_add_f32 v[78:79], v[82:83], v[80:81]
	s_waitcnt vmcnt(20)
	v_pk_mul_f32 v[80:81], v[6:7], v[122:123]
	v_add_f32_e32 v78, v78, v79
	s_nop 1
	v_add_f32_dpp v78, v78, v78 quad_perm:[1,0,3,2] row_mask:0xf bank_mask:0xf bound_ctrl:1
	s_nop 1
	v_add_f32_dpp v78, v78, v78 quad_perm:[2,3,0,1] row_mask:0xf bank_mask:0xf bound_ctrl:1
	s_nop 1
	v_add_f32_dpp v78, v78, v78 row_half_mirror row_mask:0xf bank_mask:0xf bound_ctrl:1
	s_nop 1
	v_add_f32_dpp v93, v78, v78 row_mirror row_mask:0xf bank_mask:0xf bound_ctrl:1
	v_pk_mul_f32 v[78:79], v[8:9], v[124:125]
	v_mul_f32_e32 v95, 0x3e38aa3b, v93
	v_pk_mov_b32 v[82:83], v[80:81], v[78:79] op_sel:[1,0]
	v_mov_b32_e32 v81, v79
	v_pk_add_f32 v[78:79], v[82:83], v[80:81]
	s_waitcnt vmcnt(19)
	v_pk_mul_f32 v[80:81], v[6:7], v[126:127]
	v_add_f32_e32 v78, v78, v79
	s_nop 1
	v_add_f32_dpp v78, v78, v78 quad_perm:[1,0,3,2] row_mask:0xf bank_mask:0xf bound_ctrl:1
	s_nop 1
	v_add_f32_dpp v78, v78, v78 quad_perm:[2,3,0,1] row_mask:0xf bank_mask:0xf bound_ctrl:1
	s_nop 1
	v_add_f32_dpp v78, v78, v78 row_half_mirror row_mask:0xf bank_mask:0xf bound_ctrl:1
	s_nop 1
	v_add_f32_dpp v96, v78, v78 row_mirror row_mask:0xf bank_mask:0xf bound_ctrl:1
	v_mul_f32_e32 v78, 0x3e38aa3b, v96
	v_max3_f32 v85, v85, v95, v78
	v_pk_mul_f32 v[78:79], v[8:9], v[128:129]
	s_nop 0
	v_pk_mov_b32 v[82:83], v[80:81], v[78:79] op_sel:[1,0]
	v_mov_b32_e32 v81, v79
	v_pk_add_f32 v[78:79], v[82:83], v[80:81]
	s_waitcnt vmcnt(18)
	v_pk_mul_f32 v[80:81], v[6:7], v[130:131]
	v_add_f32_e32 v78, v78, v79
	s_nop 1
	v_add_f32_dpp v78, v78, v78 quad_perm:[1,0,3,2] row_mask:0xf bank_mask:0xf bound_ctrl:1
	s_nop 1
	v_add_f32_dpp v78, v78, v78 quad_perm:[2,3,0,1] row_mask:0xf bank_mask:0xf bound_ctrl:1
	s_nop 1
	v_add_f32_dpp v78, v78, v78 row_half_mirror row_mask:0xf bank_mask:0xf bound_ctrl:1
	s_nop 1
	v_add_f32_dpp v95, v78, v78 row_mirror row_mask:0xf bank_mask:0xf bound_ctrl:1
	v_pk_mul_f32 v[78:79], v[8:9], v[132:133]
	v_mul_f32_e32 v97, 0x3e38aa3b, v95
	v_pk_mov_b32 v[82:83], v[80:81], v[78:79] op_sel:[1,0]
	v_mov_b32_e32 v81, v79
	v_pk_add_f32 v[78:79], v[82:83], v[80:81]
	s_waitcnt vmcnt(17)
	v_pk_mul_f32 v[80:81], v[6:7], v[134:135]
	v_add_f32_e32 v78, v78, v79
	s_nop 1
	v_add_f32_dpp v78, v78, v78 quad_perm:[1,0,3,2] row_mask:0xf bank_mask:0xf bound_ctrl:1
	s_nop 1
	v_add_f32_dpp v78, v78, v78 quad_perm:[2,3,0,1] row_mask:0xf bank_mask:0xf bound_ctrl:1
	s_nop 1
	v_add_f32_dpp v78, v78, v78 row_half_mirror row_mask:0xf bank_mask:0xf bound_ctrl:1
	s_nop 1
	v_add_f32_dpp v98, v78, v78 row_mirror row_mask:0xf bank_mask:0xf bound_ctrl:1
	v_mul_f32_e32 v78, 0x3e38aa3b, v98
	v_max3_f32 v85, v85, v97, v78
	v_pk_mul_f32 v[78:79], v[8:9], v[136:137]
	s_nop 0
	v_pk_mov_b32 v[82:83], v[80:81], v[78:79] op_sel:[1,0]
	v_mov_b32_e32 v81, v79
	v_pk_add_f32 v[78:79], v[82:83], v[80:81]
	s_waitcnt vmcnt(16)
	v_pk_mul_f32 v[80:81], v[6:7], v[138:139]
	v_add_f32_e32 v78, v78, v79
	s_nop 1
	v_add_f32_dpp v78, v78, v78 quad_perm:[1,0,3,2] row_mask:0xf bank_mask:0xf bound_ctrl:1
	s_nop 1
	v_add_f32_dpp v78, v78, v78 quad_perm:[2,3,0,1] row_mask:0xf bank_mask:0xf bound_ctrl:1
	s_nop 1
	v_add_f32_dpp v78, v78, v78 row_half_mirror row_mask:0xf bank_mask:0xf bound_ctrl:1
	s_nop 1
	v_add_f32_dpp v97, v78, v78 row_mirror row_mask:0xf bank_mask:0xf bound_ctrl:1
	v_pk_mul_f32 v[78:79], v[8:9], v[140:141]
	v_mul_f32_e32 v99, 0x3e38aa3b, v97
	v_pk_mov_b32 v[82:83], v[80:81], v[78:79] op_sel:[1,0]
	v_mov_b32_e32 v81, v79
	v_pk_add_f32 v[78:79], v[82:83], v[80:81]
	s_nop 0
	v_add_f32_e32 v78, v78, v79
	s_nop 1
	v_add_f32_dpp v78, v78, v78 quad_perm:[1,0,3,2] row_mask:0xf bank_mask:0xf bound_ctrl:1
	s_nop 1
	v_add_f32_dpp v78, v78, v78 quad_perm:[2,3,0,1] row_mask:0xf bank_mask:0xf bound_ctrl:1
	s_nop 1
	v_add_f32_dpp v78, v78, v78 row_half_mirror row_mask:0xf bank_mask:0xf bound_ctrl:1
	s_nop 1
	v_add_f32_dpp v79, v78, v78 row_mirror row_mask:0xf bank_mask:0xf bound_ctrl:1
	v_mul_f32_e32 v78, 0x3e38aa3b, v79
	v_max3_f32 v78, v85, v99, v78
	v_mov_b32_e32 v80, v78
	s_nop 1
	v_permlane16_swap_b32_e32 v78, v80
	v_max_f32_e32 v80, v80, v80
	v_max_f32_e32 v78, v78, v78
	v_max_f32_e32 v78, v78, v80
	v_mov_b32_e32 v80, v78
	s_nop 1
	v_permlane32_swap_b32_e32 v78, v80
	v_max3_f32 v157, v156, v78, v80
	v_fma_f32 v80, v154, s41, -v157
	v_sub_f32_e32 v78, v156, v157
	v_exp_f32_e32 v80, v80
	v_exp_f32_e32 v78, v78
	v_mov_b32_e32 v85, v80
	v_fmac_f32_e32 v85, v69, v78
	s_waitcnt vmcnt(15)
	v_pk_mul_f32 v[82:83], v[144:145], v[80:81] op_sel_hi:[1,0]
	v_pk_mul_f32 v[80:81], v[142:143], v[80:81] op_sel_hi:[1,0]
	v_fma_f32 v69, v84, s41, -v157
	v_pk_fma_f32 v[74:75], v[74:75], v[78:79], v[80:81] op_sel_hi:[1,0,1]
	v_pk_fma_f32 v[72:73], v[72:73], v[78:79], v[82:83] op_sel_hi:[1,0,1]
	v_exp_f32_e32 v78, v69
	s_nop 0
	v_add_f32_e32 v69, v78, v85
	s_waitcnt vmcnt(14)
	v_pk_fma_f32 v[72:73], v[148:149], v[78:79], v[72:73] op_sel_hi:[1,0,1]
	v_pk_fma_f32 v[74:75], v[146:147], v[78:79], v[74:75] op_sel_hi:[1,0,1]
	v_fma_f32 v78, v86, s41, -v157
	v_exp_f32_e32 v78, v78
	s_nop 0
	v_add_f32_e32 v69, v78, v69
	s_waitcnt vmcnt(13)
	v_pk_fma_f32 v[74:75], v[150:151], v[78:79], v[74:75] op_sel_hi:[1,0,1]
	v_pk_fma_f32 v[72:73], v[152:153], v[78:79], v[72:73] op_sel_hi:[1,0,1]
	v_fma_f32 v78, v88, s41, -v157
	v_exp_f32_e32 v78, v78
	s_waitcnt vmcnt(12)
	v_pk_fma_f32 v[64:65], v[64:65], v[78:79], v[72:73] op_sel_hi:[1,0,1]
	v_fma_f32 v72, v87, s41, -v157
	v_exp_f32_e32 v72, v72
	v_pk_fma_f32 v[62:63], v[62:63], v[78:79], v[74:75] op_sel_hi:[1,0,1]
	v_add_f32_e32 v69, v78, v69
	s_waitcnt vmcnt(11)
	v_pk_fma_f32 v[58:59], v[58:59], v[72:73], v[62:63] op_sel_hi:[1,0,1]
	v_fma_f32 v62, v90, s41, -v157
	v_exp_f32_e32 v62, v62
	v_add_f32_e32 v69, v72, v69
	v_pk_fma_f32 v[60:61], v[60:61], v[72:73], v[64:65] op_sel_hi:[1,0,1]
	v_add_f32_e32 v63, v62, v69
	s_waitcnt vmcnt(10)
	v_pk_fma_f32 v[54:55], v[54:55], v[62:63], v[58:59] op_sel_hi:[1,0,1]
	v_fma_f32 v58, v89, s41, -v157
	v_exp_f32_e32 v58, v58
	v_pk_fma_f32 v[56:57], v[56:57], v[62:63], v[60:61] op_sel_hi:[1,0,1]
	v_add_f32_e32 v59, v58, v63
	s_waitcnt vmcnt(9)
	v_pk_fma_f32 v[50:51], v[50:51], v[58:59], v[54:55] op_sel_hi:[1,0,1]
	v_fma_f32 v54, v92, s41, -v157
	v_exp_f32_e32 v54, v54
	v_pk_fma_f32 v[52:53], v[52:53], v[58:59], v[56:57] op_sel_hi:[1,0,1]
	v_add_f32_e32 v55, v54, v59
	s_waitcnt vmcnt(8)
	v_pk_fma_f32 v[46:47], v[46:47], v[54:55], v[50:51] op_sel_hi:[1,0,1]
	v_fma_f32 v50, v91, s41, -v157
	v_exp_f32_e32 v50, v50
	v_pk_fma_f32 v[48:49], v[48:49], v[54:55], v[52:53] op_sel_hi:[1,0,1]
	v_add_f32_e32 v51, v50, v55
	s_waitcnt vmcnt(7)
	v_pk_fma_f32 v[42:43], v[42:43], v[50:51], v[46:47] op_sel_hi:[1,0,1]
	v_fma_f32 v46, v94, s41, -v157
	v_exp_f32_e32 v46, v46
	v_pk_fma_f32 v[44:45], v[44:45], v[50:51], v[48:49] op_sel_hi:[1,0,1]
	v_add_f32_e32 v47, v46, v51
	s_waitcnt vmcnt(6)
	v_pk_fma_f32 v[38:39], v[38:39], v[46:47], v[42:43] op_sel_hi:[1,0,1]
	v_fma_f32 v42, v93, s41, -v157
	v_exp_f32_e32 v42, v42
	v_pk_fma_f32 v[40:41], v[40:41], v[46:47], v[44:45] op_sel_hi:[1,0,1]
	v_add_f32_e32 v43, v42, v47
	s_waitcnt vmcnt(5)
	v_pk_fma_f32 v[34:35], v[34:35], v[42:43], v[38:39] op_sel_hi:[1,0,1]
	v_fma_f32 v38, v96, s41, -v157
	v_exp_f32_e32 v38, v38
	v_pk_fma_f32 v[36:37], v[36:37], v[42:43], v[40:41] op_sel_hi:[1,0,1]
	v_add_f32_e32 v39, v38, v43
	s_waitcnt vmcnt(4)
	v_pk_fma_f32 v[30:31], v[30:31], v[38:39], v[34:35] op_sel_hi:[1,0,1]
	v_fma_f32 v34, v95, s41, -v157
	v_exp_f32_e32 v34, v34
	v_pk_fma_f32 v[32:33], v[32:33], v[38:39], v[36:37] op_sel_hi:[1,0,1]
	v_add_f32_e32 v35, v34, v39
	s_waitcnt vmcnt(3)
	v_pk_fma_f32 v[26:27], v[26:27], v[34:35], v[30:31] op_sel_hi:[1,0,1]
	v_fma_f32 v30, v98, s41, -v157
	v_exp_f32_e32 v30, v30
	v_pk_fma_f32 v[28:29], v[28:29], v[34:35], v[32:33] op_sel_hi:[1,0,1]
	v_add_f32_e32 v31, v30, v35
	s_waitcnt vmcnt(2)
	v_pk_fma_f32 v[22:23], v[22:23], v[30:31], v[26:27] op_sel_hi:[1,0,1]
	v_fma_f32 v26, v97, s41, -v157
	v_exp_f32_e32 v26, v26
	v_pk_fma_f32 v[24:25], v[24:25], v[30:31], v[28:29] op_sel_hi:[1,0,1]
	v_add_f32_e32 v27, v26, v31
	s_waitcnt vmcnt(1)
	v_pk_fma_f32 v[18:19], v[18:19], v[26:27], v[22:23] op_sel_hi:[1,0,1]
	v_fma_f32 v22, v79, s41, -v157
	s_lshl_b64 s[98:99], s[4:5], 2
	s_add_u32 s98, s98, s84
	s_addc_u32 s99, s99, s85
	global_load_dwordx4 v[78:81], v254, s[98:99] nt
	s_add_u32 s98, s98, 0x2000
	s_addc_u32 s99, s99, 0
	global_load_dwordx4 v[82:85], v254, s[98:99] nt
	s_add_u32 s98, s98, 0x2000
	s_addc_u32 s99, s99, 0
	global_load_dwordx4 v[86:89], v254, s[98:99] nt
	s_add_u32 s98, s98, 0x2000
	s_addc_u32 s99, s99, 0
	global_load_dwordx4 v[90:93], v254, s[98:99] nt
	s_add_u32 s98, s98, 0x2000
	s_addc_u32 s99, s99, 0
	global_load_dwordx4 v[94:97], v254, s[98:99] nt
	s_add_u32 s98, s98, 0x2000
	s_addc_u32 s99, s99, 0
	global_load_dwordx4 v[98:101], v254, s[98:99] nt
	s_add_u32 s98, s98, 0x2000
	s_addc_u32 s99, s99, 0
	global_load_dwordx4 v[102:105], v254, s[98:99] nt
	s_add_u32 s98, s98, 0x2000
	s_addc_u32 s99, s99, 0
	global_load_dwordx4 v[106:109], v254, s[98:99] nt
	s_add_u32 s98, s98, 0x2000
	s_addc_u32 s99, s99, 0
	global_load_dwordx4 v[110:113], v254, s[98:99] nt
	s_add_u32 s98, s98, 0x2000
	s_addc_u32 s99, s99, 0
	global_load_dwordx4 v[114:117], v254, s[98:99] nt
	s_add_u32 s98, s98, 0x2000
	s_addc_u32 s99, s99, 0
	global_load_dwordx4 v[118:121], v254, s[98:99] nt
	s_add_u32 s98, s98, 0x2000
	s_addc_u32 s99, s99, 0
	global_load_dwordx4 v[122:125], v254, s[98:99] nt
	s_add_u32 s98, s98, 0x2000
	s_addc_u32 s99, s99, 0
	global_load_dwordx4 v[126:129], v254, s[98:99] nt
	s_add_u32 s98, s98, 0x2000
	s_addc_u32 s99, s99, 0
	global_load_dwordx4 v[130:133], v254, s[98:99] nt
	s_add_u32 s98, s98, 0x2000
	s_addc_u32 s99, s99, 0
	global_load_dwordx4 v[134:137], v254, s[98:99] nt
	s_add_u32 s98, s98, 0x2000
	s_addc_u32 s99, s99, 0
	global_load_dwordx4 v[138:141], v254, s[98:99] nt
	s_lshl_b64 s[100:101], s[4:5], 2
	s_add_u32 s100, s100, s86
	s_addc_u32 s101, s101, s87
	global_load_dwordx4 v[142:145], v254, s[100:101] nt
	s_add_u32 s100, s100, 0x2000
	s_addc_u32 s101, s101, 0
	global_load_dwordx4 v[146:149], v254, s[100:101] nt
	s_add_u32 s100, s100, 0x2000
	s_addc_u32 s101, s101, 0
	global_load_dwordx4 v[150:153], v254, s[100:101] nt
	s_add_u32 s100, s100, 0x2000
	s_addc_u32 s101, s101, 0
	global_load_dwordx4 v[62:65], v254, s[100:101] nt
	s_add_u32 s100, s100, 0x2000
	s_addc_u32 s101, s101, 0
	global_load_dwordx4 v[58:61], v254, s[100:101] nt
	s_add_u32 s100, s100, 0x2000
	s_addc_u32 s101, s101, 0
	global_load_dwordx4 v[54:57], v254, s[100:101] nt
	s_add_u32 s100, s100, 0x2000
	s_addc_u32 s101, s101, 0
	global_load_dwordx4 v[50:53], v254, s[100:101] nt
	s_add_u32 s100, s100, 0x2000
	s_addc_u32 s101, s101, 0
	global_load_dwordx4 v[46:49], v254, s[100:101] nt
	s_add_u32 s100, s100, 0x2000
	s_addc_u32 s101, s101, 0
	global_load_dwordx4 v[42:45], v254, s[100:101] nt
	s_add_u32 s100, s100, 0x2000
	s_addc_u32 s101, s101, 0
	global_load_dwordx4 v[38:41], v254, s[100:101] nt
	s_add_u32 s100, s100, 0x2000
	s_addc_u32 s101, s101, 0
	global_load_dwordx4 v[34:37], v254, s[100:101] nt
	s_add_u32 s100, s100, 0x2000
	s_addc_u32 s101, s101, 0
	global_load_dwordx4 v[30:33], v254, s[100:101] nt
	v_exp_f32_e32 v22, v22
	v_pk_fma_f32 v[20:21], v[20:21], v[26:27], v[24:25] op_sel_hi:[1,0,1]
	s_waitcnt vmcnt(28)
	v_pk_fma_f32 v[74:75], v[14:15], v[22:23], v[18:19] op_sel_hi:[1,0,1]
	v_pk_fma_f32 v[72:73], v[16:17], v[22:23], v[20:21] op_sel_hi:[1,0,1]
	v_add_f32_e32 v69, v22, v27
	s_add_u32 s100, s100, 0x2000
	s_addc_u32 s101, s101, 0
	global_load_dwordx4 v[26:29], v254, s[100:101] nt
	s_add_u32 s100, s100, 0x2000
	s_addc_u32 s101, s101, 0
	global_load_dwordx4 v[22:25], v254, s[100:101] nt
	s_add_u32 s100, s100, 0x2000
	s_addc_u32 s101, s101, 0
	global_load_dwordx4 v[18:21], v254, s[100:101] nt
	s_add_u32 s100, s100, 0x2000
	s_addc_u32 s101, s101, 0
	global_load_dwordx4 v[14:17], v254, s[100:101] nt
	s_waitcnt vmcnt(31)
	v_pk_mul_f32 v[80:81], v[8:9], v[80:81]
	v_pk_mul_f32 v[78:79], v[6:7], v[78:79]
	s_nop 0
	v_pk_mov_b32 v[154:155], v[78:79], v[80:81] op_sel:[1,0]
	v_mov_b32_e32 v79, v81
	v_pk_add_f32 v[78:79], v[154:155], v[78:79]
	s_nop 0
	v_add_f32_e32 v78, v78, v79
	s_nop 1
	v_add_f32_dpp v78, v78, v78 quad_perm:[1,0,3,2] row_mask:0xf bank_mask:0xf bound_ctrl:1
	s_nop 1
	v_add_f32_dpp v78, v78, v78 quad_perm:[2,3,0,1] row_mask:0xf bank_mask:0xf bound_ctrl:1
	s_nop 1
	v_add_f32_dpp v78, v78, v78 row_half_mirror row_mask:0xf bank_mask:0xf bound_ctrl:1
	s_waitcnt vmcnt(30)
	v_pk_mul_f32 v[80:81], v[6:7], v[82:83]
	v_add_f32_dpp v154, v78, v78 row_mirror row_mask:0xf bank_mask:0xf bound_ctrl:1
	v_pk_mul_f32 v[78:79], v[8:9], v[84:85]
	s_nop 0
	v_pk_mov_b32 v[82:83], v[80:81], v[78:79] op_sel:[1,0]
	v_mov_b32_e32 v81, v79
	v_pk_add_f32 v[78:79], v[82:83], v[80:81]
	s_nop 0
	v_add_f32_e32 v78, v78, v79
	v_mul_f32_e32 v155, 0x3e38aa3b, v154
	s_nop 0
	v_add_f32_dpp v78, v78, v78 quad_perm:[1,0,3,2] row_mask:0xf bank_mask:0xf bound_ctrl:1
	s_waitcnt vmcnt(29)
	v_pk_mul_f32 v[80:81], v[6:7], v[86:87]
	v_add_f32_dpp v78, v78, v78 quad_perm:[2,3,0,1] row_mask:0xf bank_mask:0xf bound_ctrl:1
	s_nop 1
	v_add_f32_dpp v78, v78, v78 row_half_mirror row_mask:0xf bank_mask:0xf bound_ctrl:1
	s_nop 1
	v_add_f32_dpp v84, v78, v78 row_mirror row_mask:0xf bank_mask:0xf bound_ctrl:1
	v_mul_f32_e32 v78, 0x3e38aa3b, v84
	v_max3_f32 v85, v155, s42, v78
	v_pk_mul_f32 v[78:79], v[8:9], v[88:89]
	s_nop 0
	v_pk_mov_b32 v[82:83], v[80:81], v[78:79] op_sel:[1,0]
	v_mov_b32_e32 v81, v79
	v_pk_add_f32 v[78:79], v[82:83], v[80:81]
	s_waitcnt vmcnt(28)
	v_pk_mul_f32 v[80:81], v[6:7], v[90:91]
	v_add_f32_e32 v78, v78, v79
	s_nop 1
	v_add_f32_dpp v78, v78, v78 quad_perm:[1,0,3,2] row_mask:0xf bank_mask:0xf bound_ctrl:1
	s_nop 1
	v_add_f32_dpp v78, v78, v78 quad_perm:[2,3,0,1] row_mask:0xf bank_mask:0xf bound_ctrl:1
	s_nop 1
	v_add_f32_dpp v78, v78, v78 row_half_mirror row_mask:0xf bank_mask:0xf bound_ctrl:1
	s_nop 1
	v_add_f32_dpp v86, v78, v78 row_mirror row_mask:0xf bank_mask:0xf bound_ctrl:1
	v_pk_mul_f32 v[78:79], v[8:9], v[92:93]
	v_mul_f32_e32 v87, 0x3e38aa3b, v86
	v_pk_mov_b32 v[82:83], v[80:81], v[78:79] op_sel:[1,0]
	v_mov_b32_e32 v81, v79
	v_pk_add_f32 v[78:79], v[82:83], v[80:81]
	s_waitcnt vmcnt(27)
	v_pk_mul_f32 v[80:81], v[6:7], v[94:95]
	v_add_f32_e32 v78, v78, v79
	s_nop 1
	v_add_f32_dpp v78, v78, v78 quad_perm:[1,0,3,2] row_mask:0xf bank_mask:0xf bound_ctrl:1
	s_nop 1
	v_add_f32_dpp v78, v78, v78 quad_perm:[2,3,0,1] row_mask:0xf bank_mask:0xf bound_ctrl:1
	s_nop 1
	v_add_f32_dpp v78, v78, v78 row_half_mirror row_mask:0xf bank_mask:0xf bound_ctrl:1
	s_nop 1
	v_add_f32_dpp v88, v78, v78 row_mirror row_mask:0xf bank_mask:0xf bound_ctrl:1
	v_mul_f32_e32 v78, 0x3e38aa3b, v88
	v_max3_f32 v85, v85, v87, v78
	v_pk_mul_f32 v[78:79], v[8:9], v[96:97]
	s_nop 0
	v_pk_mov_b32 v[82:83], v[80:81], v[78:79] op_sel:[1,0]
	v_mov_b32_e32 v81, v79
	v_pk_add_f32 v[78:79], v[82:83], v[80:81]
	s_waitcnt vmcnt(26)
	v_pk_mul_f32 v[80:81], v[6:7], v[98:99]
	v_add_f32_e32 v78, v78, v79
	s_nop 1
	v_add_f32_dpp v78, v78, v78 quad_perm:[1,0,3,2] row_mask:0xf bank_mask:0xf bound_ctrl:1
	s_nop 1
	v_add_f32_dpp v78, v78, v78 quad_perm:[2,3,0,1] row_mask:0xf bank_mask:0xf bound_ctrl:1
	s_nop 1
	v_add_f32_dpp v78, v78, v78 row_half_mirror row_mask:0xf bank_mask:0xf bound_ctrl:1
	s_nop 1
	v_add_f32_dpp v87, v78, v78 row_mirror row_mask:0xf bank_mask:0xf bound_ctrl:1
	v_pk_mul_f32 v[78:79], v[8:9], v[100:101]
	v_mul_f32_e32 v89, 0x3e38aa3b, v87
	v_pk_mov_b32 v[82:83], v[80:81], v[78:79] op_sel:[1,0]
	v_mov_b32_e32 v81, v79
	v_pk_add_f32 v[78:79], v[82:83], v[80:81]
	s_waitcnt vmcnt(25)
	v_pk_mul_f32 v[80:81], v[6:7], v[102:103]
	v_add_f32_e32 v78, v78, v79
	s_nop 1
	v_add_f32_dpp v78, v78, v78 quad_perm:[1,0,3,2] row_mask:0xf bank_mask:0xf bound_ctrl:1
	s_nop 1
	v_add_f32_dpp v78, v78, v78 quad_perm:[2,3,0,1] row_mask:0xf bank_mask:0xf bound_ctrl:1
	s_nop 1
	v_add_f32_dpp v78, v78, v78 row_half_mirror row_mask:0xf bank_mask:0xf bound_ctrl:1
	s_nop 1
	v_add_f32_dpp v90, v78, v78 row_mirror row_mask:0xf bank_mask:0xf bound_ctrl:1
	v_mul_f32_e32 v78, 0x3e38aa3b, v90
	v_max3_f32 v85, v85, v89, v78
	v_pk_mul_f32 v[78:79], v[8:9], v[104:105]
	s_nop 0
	v_pk_mov_b32 v[82:83], v[80:81], v[78:79] op_sel:[1,0]
	v_mov_b32_e32 v81, v79
	v_pk_add_f32 v[78:79], v[82:83], v[80:81]
	s_waitcnt vmcnt(24)
	v_pk_mul_f32 v[80:81], v[6:7], v[106:107]
	v_add_f32_e32 v78, v78, v79
	s_nop 1
	v_add_f32_dpp v78, v78, v78 quad_perm:[1,0,3,2] row_mask:0xf bank_mask:0xf bound_ctrl:1
	s_nop 1
	v_add_f32_dpp v78, v78, v78 quad_perm:[2,3,0,1] row_mask:0xf bank_mask:0xf bound_ctrl:1
	s_nop 1
	v_add_f32_dpp v78, v78, v78 row_half_mirror row_mask:0xf bank_mask:0xf bound_ctrl:1
	s_nop 1
	v_add_f32_dpp v89, v78, v78 row_mirror row_mask:0xf bank_mask:0xf bound_ctrl:1
	v_pk_mul_f32 v[78:79], v[8:9], v[108:109]
	v_mul_f32_e32 v91, 0x3e38aa3b, v89
	v_pk_mov_b32 v[82:83], v[80:81], v[78:79] op_sel:[1,0]
	v_mov_b32_e32 v81, v79
	v_pk_add_f32 v[78:79], v[82:83], v[80:81]
	s_waitcnt vmcnt(23)
	v_pk_mul_f32 v[80:81], v[6:7], v[110:111]
	v_add_f32_e32 v78, v78, v79
	s_nop 1
	v_add_f32_dpp v78, v78, v78 quad_perm:[1,0,3,2] row_mask:0xf bank_mask:0xf bound_ctrl:1
	s_nop 1
	v_add_f32_dpp v78, v78, v78 quad_perm:[2,3,0,1] row_mask:0xf bank_mask:0xf bound_ctrl:1
	s_nop 1
	v_add_f32_dpp v78, v78, v78 row_half_mirror row_mask:0xf bank_mask:0xf bound_ctrl:1
	s_nop 1
	v_add_f32_dpp v92, v78, v78 row_mirror row_mask:0xf bank_mask:0xf bound_ctrl:1
	v_mul_f32_e32 v78, 0x3e38aa3b, v92
	v_max3_f32 v85, v85, v91, v78
	v_pk_mul_f32 v[78:79], v[8:9], v[112:113]
	s_nop 0
	v_pk_mov_b32 v[82:83], v[80:81], v[78:79] op_sel:[1,0]
	v_mov_b32_e32 v81, v79
	v_pk_add_f32 v[78:79], v[82:83], v[80:81]
	s_waitcnt vmcnt(22)
	v_pk_mul_f32 v[80:81], v[6:7], v[114:115]
	v_add_f32_e32 v78, v78, v79
	s_nop 1
	v_add_f32_dpp v78, v78, v78 quad_perm:[1,0,3,2] row_mask:0xf bank_mask:0xf bound_ctrl:1
	s_nop 1
	v_add_f32_dpp v78, v78, v78 quad_perm:[2,3,0,1] row_mask:0xf bank_mask:0xf bound_ctrl:1
	s_nop 1
	v_add_f32_dpp v78, v78, v78 row_half_mirror row_mask:0xf bank_mask:0xf bound_ctrl:1
	s_nop 1
	v_add_f32_dpp v91, v78, v78 row_mirror row_mask:0xf bank_mask:0xf bound_ctrl:1
	v_pk_mul_f32 v[78:79], v[8:9], v[116:117]
	v_mul_f32_e32 v93, 0x3e38aa3b, v91
	v_pk_mov_b32 v[82:83], v[80:81], v[78:79] op_sel:[1,0]
	v_mov_b32_e32 v81, v79
	v_pk_add_f32 v[78:79], v[82:83], v[80:81]
	s_waitcnt vmcnt(21)
	v_pk_mul_f32 v[80:81], v[6:7], v[118:119]
	v_add_f32_e32 v78, v78, v79
	s_nop 1
	v_add_f32_dpp v78, v78, v78 quad_perm:[1,0,3,2] row_mask:0xf bank_mask:0xf bound_ctrl:1
	s_nop 1
	v_add_f32_dpp v78, v78, v78 quad_perm:[2,3,0,1] row_mask:0xf bank_mask:0xf bound_ctrl:1
	s_nop 1
	v_add_f32_dpp v78, v78, v78 row_half_mirror row_mask:0xf bank_mask:0xf bound_ctrl:1
	s_nop 1
	v_add_f32_dpp v94, v78, v78 row_mirror row_mask:0xf bank_mask:0xf bound_ctrl:1
	v_mul_f32_e32 v78, 0x3e38aa3b, v94
	v_max3_f32 v85, v85, v93, v78
	v_pk_mul_f32 v[78:79], v[8:9], v[120:121]
	s_nop 0
	v_pk_mov_b32 v[82:83], v[80:81], v[78:79] op_sel:[1,0]
	v_mov_b32_e32 v81, v79
	v_pk_add_f32 v[78:79], v[82:83], v[80:81]
	s_waitcnt vmcnt(20)
	v_pk_mul_f32 v[80:81], v[6:7], v[122:123]
	v_add_f32_e32 v78, v78, v79
	s_nop 1
	v_add_f32_dpp v78, v78, v78 quad_perm:[1,0,3,2] row_mask:0xf bank_mask:0xf bound_ctrl:1
	s_nop 1
	v_add_f32_dpp v78, v78, v78 quad_perm:[2,3,0,1] row_mask:0xf bank_mask:0xf bound_ctrl:1
	s_nop 1
	v_add_f32_dpp v78, v78, v78 row_half_mirror row_mask:0xf bank_mask:0xf bound_ctrl:1
	s_nop 1
	v_add_f32_dpp v93, v78, v78 row_mirror row_mask:0xf bank_mask:0xf bound_ctrl:1
	v_pk_mul_f32 v[78:79], v[8:9], v[124:125]
	v_mul_f32_e32 v95, 0x3e38aa3b, v93
	v_pk_mov_b32 v[82:83], v[80:81], v[78:79] op_sel:[1,0]
	v_mov_b32_e32 v81, v79
	v_pk_add_f32 v[78:79], v[82:83], v[80:81]
	s_waitcnt vmcnt(19)
	v_pk_mul_f32 v[80:81], v[6:7], v[126:127]
	v_add_f32_e32 v78, v78, v79
	s_nop 1
	v_add_f32_dpp v78, v78, v78 quad_perm:[1,0,3,2] row_mask:0xf bank_mask:0xf bound_ctrl:1
	s_nop 1
	v_add_f32_dpp v78, v78, v78 quad_perm:[2,3,0,1] row_mask:0xf bank_mask:0xf bound_ctrl:1
	s_nop 1
	v_add_f32_dpp v78, v78, v78 row_half_mirror row_mask:0xf bank_mask:0xf bound_ctrl:1
	s_nop 1
	v_add_f32_dpp v96, v78, v78 row_mirror row_mask:0xf bank_mask:0xf bound_ctrl:1
	v_mul_f32_e32 v78, 0x3e38aa3b, v96
	v_max3_f32 v85, v85, v95, v78
	v_pk_mul_f32 v[78:79], v[8:9], v[128:129]
	s_nop 0
	v_pk_mov_b32 v[82:83], v[80:81], v[78:79] op_sel:[1,0]
	v_mov_b32_e32 v81, v79
	v_pk_add_f32 v[78:79], v[82:83], v[80:81]
	s_waitcnt vmcnt(18)
	v_pk_mul_f32 v[80:81], v[6:7], v[130:131]
	v_add_f32_e32 v78, v78, v79
	s_nop 1
	v_add_f32_dpp v78, v78, v78 quad_perm:[1,0,3,2] row_mask:0xf bank_mask:0xf bound_ctrl:1
	s_nop 1
	v_add_f32_dpp v78, v78, v78 quad_perm:[2,3,0,1] row_mask:0xf bank_mask:0xf bound_ctrl:1
	s_nop 1
	v_add_f32_dpp v78, v78, v78 row_half_mirror row_mask:0xf bank_mask:0xf bound_ctrl:1
	s_nop 1
	v_add_f32_dpp v95, v78, v78 row_mirror row_mask:0xf bank_mask:0xf bound_ctrl:1
	v_pk_mul_f32 v[78:79], v[8:9], v[132:133]
	v_mul_f32_e32 v97, 0x3e38aa3b, v95
	v_pk_mov_b32 v[82:83], v[80:81], v[78:79] op_sel:[1,0]
	v_mov_b32_e32 v81, v79
	v_pk_add_f32 v[78:79], v[82:83], v[80:81]
	s_waitcnt vmcnt(17)
	v_pk_mul_f32 v[80:81], v[6:7], v[134:135]
	v_add_f32_e32 v78, v78, v79
	s_nop 1
	v_add_f32_dpp v78, v78, v78 quad_perm:[1,0,3,2] row_mask:0xf bank_mask:0xf bound_ctrl:1
	s_nop 1
	v_add_f32_dpp v78, v78, v78 quad_perm:[2,3,0,1] row_mask:0xf bank_mask:0xf bound_ctrl:1
	s_nop 1
	v_add_f32_dpp v78, v78, v78 row_half_mirror row_mask:0xf bank_mask:0xf bound_ctrl:1
	s_nop 1
	v_add_f32_dpp v98, v78, v78 row_mirror row_mask:0xf bank_mask:0xf bound_ctrl:1
	v_mul_f32_e32 v78, 0x3e38aa3b, v98
	v_max3_f32 v85, v85, v97, v78
	v_pk_mul_f32 v[78:79], v[8:9], v[136:137]
	s_nop 0
	v_pk_mov_b32 v[82:83], v[80:81], v[78:79] op_sel:[1,0]
	v_mov_b32_e32 v81, v79
	v_pk_add_f32 v[78:79], v[82:83], v[80:81]
	s_waitcnt vmcnt(16)
	v_pk_mul_f32 v[80:81], v[6:7], v[138:139]
	v_add_f32_e32 v78, v78, v79
	s_nop 1
	v_add_f32_dpp v78, v78, v78 quad_perm:[1,0,3,2] row_mask:0xf bank_mask:0xf bound_ctrl:1
	s_nop 1
	v_add_f32_dpp v78, v78, v78 quad_perm:[2,3,0,1] row_mask:0xf bank_mask:0xf bound_ctrl:1
	s_nop 1
	v_add_f32_dpp v78, v78, v78 row_half_mirror row_mask:0xf bank_mask:0xf bound_ctrl:1
	s_nop 1
	v_add_f32_dpp v97, v78, v78 row_mirror row_mask:0xf bank_mask:0xf bound_ctrl:1
	v_pk_mul_f32 v[78:79], v[8:9], v[140:141]
	v_mul_f32_e32 v99, 0x3e38aa3b, v97
	v_pk_mov_b32 v[82:83], v[80:81], v[78:79] op_sel:[1,0]
	v_mov_b32_e32 v81, v79
	v_pk_add_f32 v[78:79], v[82:83], v[80:81]
	s_nop 0
	v_add_f32_e32 v78, v78, v79
	s_nop 1
	v_add_f32_dpp v78, v78, v78 quad_perm:[1,0,3,2] row_mask:0xf bank_mask:0xf bound_ctrl:1
	s_nop 1
	v_add_f32_dpp v78, v78, v78 quad_perm:[2,3,0,1] row_mask:0xf bank_mask:0xf bound_ctrl:1
	s_nop 1
	v_add_f32_dpp v78, v78, v78 row_half_mirror row_mask:0xf bank_mask:0xf bound_ctrl:1
	s_nop 1
	v_add_f32_dpp v79, v78, v78 row_mirror row_mask:0xf bank_mask:0xf bound_ctrl:1
	v_mul_f32_e32 v78, 0x3e38aa3b, v79
	v_max3_f32 v78, v85, v99, v78
	v_mov_b32_e32 v80, v78
	s_nop 1
	v_permlane16_swap_b32_e32 v78, v80
	v_max_f32_e32 v80, v80, v80
	v_max_f32_e32 v78, v78, v78
	v_max_f32_e32 v78, v78, v80
	v_mov_b32_e32 v80, v78
	s_nop 1
	v_permlane32_swap_b32_e32 v78, v80
	v_max3_f32 v156, v157, v78, v80
	v_fma_f32 v80, v154, s41, -v156
	v_sub_f32_e32 v78, v157, v156
	v_exp_f32_e32 v80, v80
	v_exp_f32_e32 v78, v78
	v_mov_b32_e32 v85, v80
	v_fmac_f32_e32 v85, v69, v78
	s_waitcnt vmcnt(15)
	v_pk_mul_f32 v[82:83], v[144:145], v[80:81] op_sel_hi:[1,0]
	v_pk_mul_f32 v[80:81], v[142:143], v[80:81] op_sel_hi:[1,0]
	v_fma_f32 v69, v84, s41, -v156
	v_pk_fma_f32 v[74:75], v[74:75], v[78:79], v[80:81] op_sel_hi:[1,0,1]
	v_pk_fma_f32 v[72:73], v[72:73], v[78:79], v[82:83] op_sel_hi:[1,0,1]
	v_exp_f32_e32 v78, v69
	s_nop 0
	v_add_f32_e32 v69, v78, v85
	s_waitcnt vmcnt(14)
	v_pk_fma_f32 v[72:73], v[148:149], v[78:79], v[72:73] op_sel_hi:[1,0,1]
	v_pk_fma_f32 v[74:75], v[146:147], v[78:79], v[74:75] op_sel_hi:[1,0,1]
	v_fma_f32 v78, v86, s41, -v156
	v_exp_f32_e32 v78, v78
	s_nop 0
	v_add_f32_e32 v69, v78, v69
	s_waitcnt vmcnt(13)
	v_pk_fma_f32 v[74:75], v[150:151], v[78:79], v[74:75] op_sel_hi:[1,0,1]
	v_pk_fma_f32 v[72:73], v[152:153], v[78:79], v[72:73] op_sel_hi:[1,0,1]
	v_fma_f32 v78, v88, s41, -v156
	v_exp_f32_e32 v78, v78
	s_waitcnt vmcnt(12)
	v_pk_fma_f32 v[64:65], v[64:65], v[78:79], v[72:73] op_sel_hi:[1,0,1]
	v_fma_f32 v72, v87, s41, -v156
	v_exp_f32_e32 v72, v72
	v_pk_fma_f32 v[62:63], v[62:63], v[78:79], v[74:75] op_sel_hi:[1,0,1]
	v_add_f32_e32 v69, v78, v69
	s_waitcnt vmcnt(11)
	v_pk_fma_f32 v[58:59], v[58:59], v[72:73], v[62:63] op_sel_hi:[1,0,1]
	v_fma_f32 v62, v90, s41, -v156
	v_exp_f32_e32 v62, v62
	v_add_f32_e32 v69, v72, v69
	v_pk_fma_f32 v[60:61], v[60:61], v[72:73], v[64:65] op_sel_hi:[1,0,1]
	v_add_f32_e32 v63, v62, v69
	s_waitcnt vmcnt(10)
	v_pk_fma_f32 v[54:55], v[54:55], v[62:63], v[58:59] op_sel_hi:[1,0,1]
	v_fma_f32 v58, v89, s41, -v156
	v_exp_f32_e32 v58, v58
	v_pk_fma_f32 v[56:57], v[56:57], v[62:63], v[60:61] op_sel_hi:[1,0,1]
	v_add_f32_e32 v59, v58, v63
	s_waitcnt vmcnt(9)
	v_pk_fma_f32 v[50:51], v[50:51], v[58:59], v[54:55] op_sel_hi:[1,0,1]
	v_fma_f32 v54, v92, s41, -v156
	v_exp_f32_e32 v54, v54
	v_pk_fma_f32 v[52:53], v[52:53], v[58:59], v[56:57] op_sel_hi:[1,0,1]
	v_add_f32_e32 v55, v54, v59
	s_waitcnt vmcnt(8)
	v_pk_fma_f32 v[46:47], v[46:47], v[54:55], v[50:51] op_sel_hi:[1,0,1]
	v_fma_f32 v50, v91, s41, -v156
	v_exp_f32_e32 v50, v50
	v_pk_fma_f32 v[48:49], v[48:49], v[54:55], v[52:53] op_sel_hi:[1,0,1]
	v_add_f32_e32 v51, v50, v55
	s_waitcnt vmcnt(7)
	v_pk_fma_f32 v[42:43], v[42:43], v[50:51], v[46:47] op_sel_hi:[1,0,1]
	v_fma_f32 v46, v94, s41, -v156
	v_exp_f32_e32 v46, v46
	v_pk_fma_f32 v[44:45], v[44:45], v[50:51], v[48:49] op_sel_hi:[1,0,1]
	v_add_f32_e32 v47, v46, v51
	s_waitcnt vmcnt(6)
	v_pk_fma_f32 v[38:39], v[38:39], v[46:47], v[42:43] op_sel_hi:[1,0,1]
	v_fma_f32 v42, v93, s41, -v156
	v_exp_f32_e32 v42, v42
	v_pk_fma_f32 v[40:41], v[40:41], v[46:47], v[44:45] op_sel_hi:[1,0,1]
	v_add_f32_e32 v43, v42, v47
	s_waitcnt vmcnt(5)
	v_pk_fma_f32 v[34:35], v[34:35], v[42:43], v[38:39] op_sel_hi:[1,0,1]
	v_fma_f32 v38, v96, s41, -v156
	v_exp_f32_e32 v38, v38
	v_pk_fma_f32 v[36:37], v[36:37], v[42:43], v[40:41] op_sel_hi:[1,0,1]
	v_add_f32_e32 v39, v38, v43
	s_waitcnt vmcnt(4)
	v_pk_fma_f32 v[30:31], v[30:31], v[38:39], v[34:35] op_sel_hi:[1,0,1]
	v_fma_f32 v34, v95, s41, -v156
	v_exp_f32_e32 v34, v34
	v_pk_fma_f32 v[32:33], v[32:33], v[38:39], v[36:37] op_sel_hi:[1,0,1]
	v_add_f32_e32 v35, v34, v39
	s_waitcnt vmcnt(3)
	v_pk_fma_f32 v[26:27], v[26:27], v[34:35], v[30:31] op_sel_hi:[1,0,1]
	v_fma_f32 v30, v98, s41, -v156
	v_exp_f32_e32 v30, v30
	v_pk_fma_f32 v[28:29], v[28:29], v[34:35], v[32:33] op_sel_hi:[1,0,1]
	v_add_f32_e32 v31, v30, v35
	s_waitcnt vmcnt(2)
	v_pk_fma_f32 v[22:23], v[22:23], v[30:31], v[26:27] op_sel_hi:[1,0,1]
	v_fma_f32 v26, v97, s41, -v156
	v_exp_f32_e32 v26, v26
	v_pk_fma_f32 v[24:25], v[24:25], v[30:31], v[28:29] op_sel_hi:[1,0,1]
	v_add_f32_e32 v27, v26, v31
	s_waitcnt vmcnt(1)
	v_pk_fma_f32 v[18:19], v[18:19], v[26:27], v[22:23] op_sel_hi:[1,0,1]
	v_fma_f32 v22, v79, s41, -v156
	s_lshl_b64 s[98:99], s[4:5], 2
	s_add_u32 s98, s98, s84
	s_addc_u32 s99, s99, s85
	s_add_u32 s98, s98, 0x20000
	s_addc_u32 s99, s99, 0
	global_load_dwordx4 v[78:81], v254, s[98:99] nt
	s_add_u32 s98, s98, 0x2000
	s_addc_u32 s99, s99, 0
	global_load_dwordx4 v[82:85], v254, s[98:99] nt
	s_add_u32 s98, s98, 0x2000
	s_addc_u32 s99, s99, 0
	global_load_dwordx4 v[86:89], v254, s[98:99] nt
	s_add_u32 s98, s98, 0x2000
	s_addc_u32 s99, s99, 0
	global_load_dwordx4 v[90:93], v254, s[98:99] nt
	s_add_u32 s98, s98, 0x2000
	s_addc_u32 s99, s99, 0
	global_load_dwordx4 v[94:97], v254, s[98:99] nt
	s_add_u32 s98, s98, 0x2000
	s_addc_u32 s99, s99, 0
	global_load_dwordx4 v[98:101], v254, s[98:99] nt
	s_add_u32 s98, s98, 0x2000
	s_addc_u32 s99, s99, 0
	global_load_dwordx4 v[102:105], v254, s[98:99] nt
	s_add_u32 s98, s98, 0x2000
	s_addc_u32 s99, s99, 0
	global_load_dwordx4 v[106:109], v254, s[98:99] nt
	s_add_u32 s98, s98, 0x2000
	s_addc_u32 s99, s99, 0
	global_load_dwordx4 v[110:113], v254, s[98:99] nt
	s_add_u32 s98, s98, 0x2000
	s_addc_u32 s99, s99, 0
	global_load_dwordx4 v[114:117], v254, s[98:99] nt
	s_add_u32 s98, s98, 0x2000
	s_addc_u32 s99, s99, 0
	global_load_dwordx4 v[118:121], v254, s[98:99] nt
	s_add_u32 s98, s98, 0x2000
	s_addc_u32 s99, s99, 0
	global_load_dwordx4 v[122:125], v254, s[98:99] nt
	s_add_u32 s98, s98, 0x2000
	s_addc_u32 s99, s99, 0
	global_load_dwordx4 v[126:129], v254, s[98:99] nt
	s_add_u32 s98, s98, 0x2000
	s_addc_u32 s99, s99, 0
	global_load_dwordx4 v[130:133], v254, s[98:99] nt
	s_add_u32 s98, s98, 0x2000
	s_addc_u32 s99, s99, 0
	global_load_dwordx4 v[134:137], v254, s[98:99] nt
	s_add_u32 s98, s98, 0x2000
	s_addc_u32 s99, s99, 0
	global_load_dwordx4 v[138:141], v254, s[98:99] nt
	s_lshl_b64 s[100:101], s[4:5], 2
	s_add_u32 s100, s100, s86
	s_addc_u32 s101, s101, s87
	s_add_u32 s100, s100, 0x20000
	s_addc_u32 s101, s101, 0
	global_load_dwordx4 v[142:145], v254, s[100:101] nt
	s_add_u32 s100, s100, 0x2000
	s_addc_u32 s101, s101, 0
	global_load_dwordx4 v[146:149], v254, s[100:101] nt
	s_add_u32 s100, s100, 0x2000
	s_addc_u32 s101, s101, 0
	global_load_dwordx4 v[150:153], v254, s[100:101] nt
	s_add_u32 s100, s100, 0x2000
	s_addc_u32 s101, s101, 0
	global_load_dwordx4 v[62:65], v254, s[100:101] nt
	s_add_u32 s100, s100, 0x2000
	s_addc_u32 s101, s101, 0
	global_load_dwordx4 v[58:61], v254, s[100:101] nt
	s_add_u32 s100, s100, 0x2000
	s_addc_u32 s101, s101, 0
	global_load_dwordx4 v[54:57], v254, s[100:101] nt
	s_add_u32 s100, s100, 0x2000
	s_addc_u32 s101, s101, 0
	global_load_dwordx4 v[50:53], v254, s[100:101] nt
	s_add_u32 s100, s100, 0x2000
	s_addc_u32 s101, s101, 0
	global_load_dwordx4 v[46:49], v254, s[100:101] nt
	s_add_u32 s100, s100, 0x2000
	s_addc_u32 s101, s101, 0
	global_load_dwordx4 v[42:45], v254, s[100:101] nt
	s_add_u32 s100, s100, 0x2000
	s_addc_u32 s101, s101, 0
	global_load_dwordx4 v[38:41], v254, s[100:101] nt
	s_add_u32 s100, s100, 0x2000
	s_addc_u32 s101, s101, 0
	global_load_dwordx4 v[34:37], v254, s[100:101] nt
	s_add_u32 s100, s100, 0x2000
	s_addc_u32 s101, s101, 0
	global_load_dwordx4 v[30:33], v254, s[100:101] nt
	v_exp_f32_e32 v22, v22
	v_pk_fma_f32 v[20:21], v[20:21], v[26:27], v[24:25] op_sel_hi:[1,0,1]
	s_waitcnt vmcnt(28)
	v_pk_fma_f32 v[74:75], v[14:15], v[22:23], v[18:19] op_sel_hi:[1,0,1]
	v_pk_fma_f32 v[72:73], v[16:17], v[22:23], v[20:21] op_sel_hi:[1,0,1]
	v_add_f32_e32 v69, v22, v27
	s_add_u32 s100, s100, 0x2000
	s_addc_u32 s101, s101, 0
	global_load_dwordx4 v[26:29], v254, s[100:101] nt
	s_add_u32 s100, s100, 0x2000
	s_addc_u32 s101, s101, 0
	global_load_dwordx4 v[22:25], v254, s[100:101] nt
	s_add_u32 s100, s100, 0x2000
	s_addc_u32 s101, s101, 0
	global_load_dwordx4 v[18:21], v254, s[100:101] nt
	s_add_u32 s100, s100, 0x2000
	s_addc_u32 s101, s101, 0
	global_load_dwordx4 v[14:17], v254, s[100:101] nt
	s_waitcnt vmcnt(31)
	v_pk_mul_f32 v[80:81], v[8:9], v[80:81]
	v_pk_mul_f32 v[78:79], v[6:7], v[78:79]
	s_nop 0
	v_pk_mov_b32 v[154:155], v[78:79], v[80:81] op_sel:[1,0]
	v_mov_b32_e32 v79, v81
	v_pk_add_f32 v[78:79], v[154:155], v[78:79]
	s_nop 0
	v_add_f32_e32 v78, v78, v79
	s_nop 1
	v_add_f32_dpp v78, v78, v78 quad_perm:[1,0,3,2] row_mask:0xf bank_mask:0xf bound_ctrl:1
	s_nop 1
	v_add_f32_dpp v78, v78, v78 quad_perm:[2,3,0,1] row_mask:0xf bank_mask:0xf bound_ctrl:1
	s_nop 1
	v_add_f32_dpp v78, v78, v78 row_half_mirror row_mask:0xf bank_mask:0xf bound_ctrl:1
	s_waitcnt vmcnt(30)
	v_pk_mul_f32 v[80:81], v[6:7], v[82:83]
	v_add_f32_dpp v154, v78, v78 row_mirror row_mask:0xf bank_mask:0xf bound_ctrl:1
	v_pk_mul_f32 v[78:79], v[8:9], v[84:85]
	s_nop 0
	v_pk_mov_b32 v[82:83], v[80:81], v[78:79] op_sel:[1,0]
	v_mov_b32_e32 v81, v79
	v_pk_add_f32 v[78:79], v[82:83], v[80:81]
	s_nop 0
	v_add_f32_e32 v78, v78, v79
	v_mul_f32_e32 v155, 0x3e38aa3b, v154
	s_nop 0
	v_add_f32_dpp v78, v78, v78 quad_perm:[1,0,3,2] row_mask:0xf bank_mask:0xf bound_ctrl:1
	s_waitcnt vmcnt(29)
	v_pk_mul_f32 v[80:81], v[6:7], v[86:87]
	v_add_f32_dpp v78, v78, v78 quad_perm:[2,3,0,1] row_mask:0xf bank_mask:0xf bound_ctrl:1
	s_nop 1
	v_add_f32_dpp v78, v78, v78 row_half_mirror row_mask:0xf bank_mask:0xf bound_ctrl:1
	s_nop 1
	v_add_f32_dpp v157, v78, v78 row_mirror row_mask:0xf bank_mask:0xf bound_ctrl:1
	v_mul_f32_e32 v78, 0x3e38aa3b, v157
	v_max3_f32 v84, v155, s42, v78
	v_pk_mul_f32 v[78:79], v[8:9], v[88:89]
	s_nop 0
	v_pk_mov_b32 v[82:83], v[80:81], v[78:79] op_sel:[1,0]
	v_mov_b32_e32 v81, v79
	v_pk_add_f32 v[78:79], v[82:83], v[80:81]
	s_waitcnt vmcnt(28)
	v_pk_mul_f32 v[80:81], v[6:7], v[90:91]
	v_add_f32_e32 v78, v78, v79
	s_nop 1
	v_add_f32_dpp v78, v78, v78 quad_perm:[1,0,3,2] row_mask:0xf bank_mask:0xf bound_ctrl:1
	s_nop 1
	v_add_f32_dpp v78, v78, v78 quad_perm:[2,3,0,1] row_mask:0xf bank_mask:0xf bound_ctrl:1
	s_nop 1
	v_add_f32_dpp v78, v78, v78 row_half_mirror row_mask:0xf bank_mask:0xf bound_ctrl:1
	s_nop 1
	v_add_f32_dpp v86, v78, v78 row_mirror row_mask:0xf bank_mask:0xf bound_ctrl:1
	v_pk_mul_f32 v[78:79], v[8:9], v[92:93]
	v_mul_f32_e32 v85, 0x3e38aa3b, v86
	v_pk_mov_b32 v[82:83], v[80:81], v[78:79] op_sel:[1,0]
	v_mov_b32_e32 v81, v79
	v_pk_add_f32 v[78:79], v[82:83], v[80:81]
	s_waitcnt vmcnt(27)
	v_pk_mul_f32 v[80:81], v[6:7], v[94:95]
	v_add_f32_e32 v78, v78, v79
	s_nop 1
	v_add_f32_dpp v78, v78, v78 quad_perm:[1,0,3,2] row_mask:0xf bank_mask:0xf bound_ctrl:1
	s_nop 1
	v_add_f32_dpp v78, v78, v78 quad_perm:[2,3,0,1] row_mask:0xf bank_mask:0xf bound_ctrl:1
	s_nop 1
	v_add_f32_dpp v78, v78, v78 row_half_mirror row_mask:0xf bank_mask:0xf bound_ctrl:1
	s_nop 1
	v_add_f32_dpp v87, v78, v78 row_mirror row_mask:0xf bank_mask:0xf bound_ctrl:1
	v_mul_f32_e32 v78, 0x3e38aa3b, v87
	v_max3_f32 v84, v84, v85, v78
	v_pk_mul_f32 v[78:79], v[8:9], v[96:97]
	s_nop 0
	v_pk_mov_b32 v[82:83], v[80:81], v[78:79] op_sel:[1,0]
	v_mov_b32_e32 v81, v79
	v_pk_add_f32 v[78:79], v[82:83], v[80:81]
	s_waitcnt vmcnt(26)
	v_pk_mul_f32 v[80:81], v[6:7], v[98:99]
	v_add_f32_e32 v78, v78, v79
	s_nop 1
	v_add_f32_dpp v78, v78, v78 quad_perm:[1,0,3,2] row_mask:0xf bank_mask:0xf bound_ctrl:1
	s_nop 1
	v_add_f32_dpp v78, v78, v78 quad_perm:[2,3,0,1] row_mask:0xf bank_mask:0xf bound_ctrl:1
	s_nop 1
	v_add_f32_dpp v78, v78, v78 row_half_mirror row_mask:0xf bank_mask:0xf bound_ctrl:1
	s_nop 1
	v_add_f32_dpp v88, v78, v78 row_mirror row_mask:0xf bank_mask:0xf bound_ctrl:1
	v_pk_mul_f32 v[78:79], v[8:9], v[100:101]
	v_mul_f32_e32 v85, 0x3e38aa3b, v88
	v_pk_mov_b32 v[82:83], v[80:81], v[78:79] op_sel:[1,0]
	v_mov_b32_e32 v81, v79
	v_pk_add_f32 v[78:79], v[82:83], v[80:81]
	s_waitcnt vmcnt(25)
	v_pk_mul_f32 v[80:81], v[6:7], v[102:103]
	v_add_f32_e32 v78, v78, v79
	s_nop 1
	v_add_f32_dpp v78, v78, v78 quad_perm:[1,0,3,2] row_mask:0xf bank_mask:0xf bound_ctrl:1
	s_nop 1
	v_add_f32_dpp v78, v78, v78 quad_perm:[2,3,0,1] row_mask:0xf bank_mask:0xf bound_ctrl:1
	s_nop 1
	v_add_f32_dpp v78, v78, v78 row_half_mirror row_mask:0xf bank_mask:0xf bound_ctrl:1
	s_nop 1
	v_add_f32_dpp v89, v78, v78 row_mirror row_mask:0xf bank_mask:0xf bound_ctrl:1
	v_mul_f32_e32 v78, 0x3e38aa3b, v89
	v_max3_f32 v84, v84, v85, v78
	v_pk_mul_f32 v[78:79], v[8:9], v[104:105]
	s_nop 0
	v_pk_mov_b32 v[82:83], v[80:81], v[78:79] op_sel:[1,0]
	v_mov_b32_e32 v81, v79
	v_pk_add_f32 v[78:79], v[82:83], v[80:81]
	s_waitcnt vmcnt(24)
	v_pk_mul_f32 v[80:81], v[6:7], v[106:107]
	v_add_f32_e32 v78, v78, v79
	s_nop 1
	v_add_f32_dpp v78, v78, v78 quad_perm:[1,0,3,2] row_mask:0xf bank_mask:0xf bound_ctrl:1
	s_nop 1
	v_add_f32_dpp v78, v78, v78 quad_perm:[2,3,0,1] row_mask:0xf bank_mask:0xf bound_ctrl:1
	s_nop 1
	v_add_f32_dpp v78, v78, v78 row_half_mirror row_mask:0xf bank_mask:0xf bound_ctrl:1
	s_nop 1
	v_add_f32_dpp v90, v78, v78 row_mirror row_mask:0xf bank_mask:0xf bound_ctrl:1
	v_pk_mul_f32 v[78:79], v[8:9], v[108:109]
	v_mul_f32_e32 v85, 0x3e38aa3b, v90
	v_pk_mov_b32 v[82:83], v[80:81], v[78:79] op_sel:[1,0]
	v_mov_b32_e32 v81, v79
	v_pk_add_f32 v[78:79], v[82:83], v[80:81]
	s_waitcnt vmcnt(23)
	v_pk_mul_f32 v[80:81], v[6:7], v[110:111]
	v_add_f32_e32 v78, v78, v79
	s_nop 1
	v_add_f32_dpp v78, v78, v78 quad_perm:[1,0,3,2] row_mask:0xf bank_mask:0xf bound_ctrl:1
	s_nop 1
	v_add_f32_dpp v78, v78, v78 quad_perm:[2,3,0,1] row_mask:0xf bank_mask:0xf bound_ctrl:1
	s_nop 1
	v_add_f32_dpp v78, v78, v78 row_half_mirror row_mask:0xf bank_mask:0xf bound_ctrl:1
	s_nop 1
	v_add_f32_dpp v91, v78, v78 row_mirror row_mask:0xf bank_mask:0xf bound_ctrl:1
	v_mul_f32_e32 v78, 0x3e38aa3b, v91
	v_max3_f32 v84, v84, v85, v78
	v_pk_mul_f32 v[78:79], v[8:9], v[112:113]
	s_nop 0
	v_pk_mov_b32 v[82:83], v[80:81], v[78:79] op_sel:[1,0]
	v_mov_b32_e32 v81, v79
	v_pk_add_f32 v[78:79], v[82:83], v[80:81]
	s_waitcnt vmcnt(22)
	v_pk_mul_f32 v[80:81], v[6:7], v[114:115]
	v_add_f32_e32 v78, v78, v79
	s_nop 1
	v_add_f32_dpp v78, v78, v78 quad_perm:[1,0,3,2] row_mask:0xf bank_mask:0xf bound_ctrl:1
	s_nop 1
	v_add_f32_dpp v78, v78, v78 quad_perm:[2,3,0,1] row_mask:0xf bank_mask:0xf bound_ctrl:1
	s_nop 1
	v_add_f32_dpp v78, v78, v78 row_half_mirror row_mask:0xf bank_mask:0xf bound_ctrl:1
	s_nop 1
	v_add_f32_dpp v92, v78, v78 row_mirror row_mask:0xf bank_mask:0xf bound_ctrl:1
	v_pk_mul_f32 v[78:79], v[8:9], v[116:117]
	v_mul_f32_e32 v85, 0x3e38aa3b, v92
	v_pk_mov_b32 v[82:83], v[80:81], v[78:79] op_sel:[1,0]
	v_mov_b32_e32 v81, v79
	v_pk_add_f32 v[78:79], v[82:83], v[80:81]
	s_waitcnt vmcnt(21)
	v_pk_mul_f32 v[80:81], v[6:7], v[118:119]
	v_add_f32_e32 v78, v78, v79
	s_nop 1
	v_add_f32_dpp v78, v78, v78 quad_perm:[1,0,3,2] row_mask:0xf bank_mask:0xf bound_ctrl:1
	s_nop 1
	v_add_f32_dpp v78, v78, v78 quad_perm:[2,3,0,1] row_mask:0xf bank_mask:0xf bound_ctrl:1
	s_nop 1
	v_add_f32_dpp v78, v78, v78 row_half_mirror row_mask:0xf bank_mask:0xf bound_ctrl:1
	s_nop 1
	v_add_f32_dpp v93, v78, v78 row_mirror row_mask:0xf bank_mask:0xf bound_ctrl:1
	v_mul_f32_e32 v78, 0x3e38aa3b, v93
	v_max3_f32 v84, v84, v85, v78
	v_pk_mul_f32 v[78:79], v[8:9], v[120:121]
	s_nop 0
	v_pk_mov_b32 v[82:83], v[80:81], v[78:79] op_sel:[1,0]
	v_mov_b32_e32 v81, v79
	v_pk_add_f32 v[78:79], v[82:83], v[80:81]
	s_waitcnt vmcnt(20)
	v_pk_mul_f32 v[80:81], v[6:7], v[122:123]
	v_add_f32_e32 v78, v78, v79
	v_cmp_ne_u32_e32 vcc, s0, v222
	s_nop 0
	v_add_f32_dpp v78, v78, v78 quad_perm:[1,0,3,2] row_mask:0xf bank_mask:0xf bound_ctrl:1
	v_cndmask_b32_e32 v76, v77, v76, vcc
	s_nop 0
	v_add_f32_dpp v78, v78, v78 quad_perm:[2,3,0,1] row_mask:0xf bank_mask:0xf bound_ctrl:1
	s_nop 1
	v_add_f32_dpp v78, v78, v78 row_half_mirror row_mask:0xf bank_mask:0xf bound_ctrl:1
	s_nop 1
	v_add_f32_dpp v94, v78, v78 row_mirror row_mask:0xf bank_mask:0xf bound_ctrl:1
	v_pk_mul_f32 v[78:79], v[8:9], v[124:125]
	v_mul_f32_e32 v85, 0x3e38aa3b, v94
	v_pk_mov_b32 v[82:83], v[80:81], v[78:79] op_sel:[1,0]
	v_mov_b32_e32 v81, v79
	v_pk_add_f32 v[78:79], v[82:83], v[80:81]
	s_waitcnt vmcnt(19)
	v_pk_mul_f32 v[80:81], v[6:7], v[126:127]
	v_add_f32_e32 v78, v78, v79
	s_nop 1
	v_add_f32_dpp v78, v78, v78 quad_perm:[1,0,3,2] row_mask:0xf bank_mask:0xf bound_ctrl:1
	s_nop 1
	v_add_f32_dpp v78, v78, v78 quad_perm:[2,3,0,1] row_mask:0xf bank_mask:0xf bound_ctrl:1
	s_nop 1
	v_add_f32_dpp v78, v78, v78 row_half_mirror row_mask:0xf bank_mask:0xf bound_ctrl:1
	s_nop 1
	v_add_f32_dpp v95, v78, v78 row_mirror row_mask:0xf bank_mask:0xf bound_ctrl:1
	v_mul_f32_e32 v78, 0x3e38aa3b, v95
	v_max3_f32 v84, v84, v85, v78
	v_pk_mul_f32 v[78:79], v[8:9], v[128:129]
	s_nop 0
	v_pk_mov_b32 v[82:83], v[80:81], v[78:79] op_sel:[1,0]
	v_mov_b32_e32 v81, v79
	v_pk_add_f32 v[78:79], v[82:83], v[80:81]
	s_waitcnt vmcnt(18)
	v_pk_mul_f32 v[80:81], v[6:7], v[130:131]
	v_add_f32_e32 v78, v78, v79
	s_nop 1
	v_add_f32_dpp v78, v78, v78 quad_perm:[1,0,3,2] row_mask:0xf bank_mask:0xf bound_ctrl:1
	s_nop 1
	v_add_f32_dpp v78, v78, v78 quad_perm:[2,3,0,1] row_mask:0xf bank_mask:0xf bound_ctrl:1
	s_nop 1
	v_add_f32_dpp v78, v78, v78 row_half_mirror row_mask:0xf bank_mask:0xf bound_ctrl:1
	s_nop 1
	v_add_f32_dpp v96, v78, v78 row_mirror row_mask:0xf bank_mask:0xf bound_ctrl:1
	v_pk_mul_f32 v[78:79], v[8:9], v[132:133]
	v_mul_f32_e32 v85, 0x3e38aa3b, v96
	v_pk_mov_b32 v[82:83], v[80:81], v[78:79] op_sel:[1,0]
	v_mov_b32_e32 v81, v79
	v_pk_add_f32 v[78:79], v[82:83], v[80:81]
	s_waitcnt vmcnt(17)
	v_pk_mul_f32 v[80:81], v[6:7], v[134:135]
	v_add_f32_e32 v78, v78, v79
	s_nop 1
	v_add_f32_dpp v78, v78, v78 quad_perm:[1,0,3,2] row_mask:0xf bank_mask:0xf bound_ctrl:1
	s_nop 1
	v_add_f32_dpp v78, v78, v78 quad_perm:[2,3,0,1] row_mask:0xf bank_mask:0xf bound_ctrl:1
	s_nop 1
	v_add_f32_dpp v78, v78, v78 row_half_mirror row_mask:0xf bank_mask:0xf bound_ctrl:1
	s_nop 1
	v_add_f32_dpp v97, v78, v78 row_mirror row_mask:0xf bank_mask:0xf bound_ctrl:1
	v_mul_f32_e32 v78, 0x3e38aa3b, v97
	v_max3_f32 v84, v84, v85, v78
	v_pk_mul_f32 v[78:79], v[8:9], v[136:137]
	s_nop 0
	v_pk_mov_b32 v[82:83], v[80:81], v[78:79] op_sel:[1,0]
	v_mov_b32_e32 v81, v79
	v_pk_add_f32 v[78:79], v[82:83], v[80:81]
	s_waitcnt vmcnt(16)
	v_pk_mul_f32 v[80:81], v[6:7], v[138:139]
	v_add_f32_e32 v78, v78, v79
	s_nop 1
	v_add_f32_dpp v78, v78, v78 quad_perm:[1,0,3,2] row_mask:0xf bank_mask:0xf bound_ctrl:1
	s_nop 1
	v_add_f32_dpp v78, v78, v78 quad_perm:[2,3,0,1] row_mask:0xf bank_mask:0xf bound_ctrl:1
	s_nop 1
	v_add_f32_dpp v78, v78, v78 row_half_mirror row_mask:0xf bank_mask:0xf bound_ctrl:1
	s_nop 1
	v_add_f32_dpp v98, v78, v78 row_mirror row_mask:0xf bank_mask:0xf bound_ctrl:1
	v_pk_mul_f32 v[78:79], v[8:9], v[140:141]
	v_mul_f32_e32 v85, 0x3e38aa3b, v98
	v_pk_mov_b32 v[82:83], v[80:81], v[78:79] op_sel:[1,0]
	v_mov_b32_e32 v81, v79
	v_pk_add_f32 v[78:79], v[82:83], v[80:81]
	s_nop 0
	v_add_f32_e32 v78, v78, v79
	s_nop 1
	v_add_f32_dpp v78, v78, v78 quad_perm:[1,0,3,2] row_mask:0xf bank_mask:0xf bound_ctrl:1
	s_nop 1
	v_add_f32_dpp v78, v78, v78 quad_perm:[2,3,0,1] row_mask:0xf bank_mask:0xf bound_ctrl:1
	s_nop 1
	v_add_f32_dpp v78, v78, v78 row_half_mirror row_mask:0xf bank_mask:0xf bound_ctrl:1
	s_nop 1
	v_add_f32_dpp v79, v78, v78 row_mirror row_mask:0xf bank_mask:0xf bound_ctrl:1
	v_mul_f32_e32 v78, 0x3e38aa3b, v79
	v_max3_f32 v78, v84, v85, v78
	v_mov_b32_e32 v80, v78
	s_nop 1
	v_permlane16_swap_b32_e32 v78, v80
	v_max_f32_e32 v80, v80, v80
	v_max_f32_e32 v78, v78, v78
	v_max_f32_e32 v78, v78, v80
	v_mov_b32_e32 v80, v78
	s_nop 1
	v_permlane32_swap_b32_e32 v78, v80
	v_max3_f32 v78, v156, v78, v80
	v_fma_f32 v81, v154, s41, -v78
	v_sub_f32_e32 v80, v156, v78
	v_exp_f32_e32 v82, v81
	v_exp_f32_e32 v80, v80
	v_mov_b32_e32 v81, v82
	v_fmac_f32_e32 v81, v69, v80
	s_waitcnt vmcnt(15)
	v_pk_mul_f32 v[84:85], v[144:145], v[82:83] op_sel_hi:[1,0]
	v_pk_mul_f32 v[82:83], v[142:143], v[82:83] op_sel_hi:[1,0]
	v_fma_f32 v69, v157, s41, -v78
	v_pk_fma_f32 v[74:75], v[74:75], v[80:81], v[82:83] op_sel_hi:[1,0,1]
	v_pk_fma_f32 v[72:73], v[72:73], v[80:81], v[84:85] op_sel_hi:[1,0,1]
	v_exp_f32_e32 v80, v69
	s_nop 0
	v_add_f32_e32 v69, v80, v81
	s_waitcnt vmcnt(14)
	v_pk_fma_f32 v[72:73], v[148:149], v[80:81], v[72:73] op_sel_hi:[1,0,1]
	v_pk_fma_f32 v[74:75], v[146:147], v[80:81], v[74:75] op_sel_hi:[1,0,1]
	v_fma_f32 v80, v86, s41, -v78
	v_exp_f32_e32 v80, v80
	s_nop 0
	v_add_f32_e32 v69, v80, v69
	s_waitcnt vmcnt(13)
	v_pk_fma_f32 v[74:75], v[150:151], v[80:81], v[74:75] op_sel_hi:[1,0,1]
	v_pk_fma_f32 v[72:73], v[152:153], v[80:81], v[72:73] op_sel_hi:[1,0,1]
	v_fma_f32 v80, v87, s41, -v78
	v_exp_f32_e32 v80, v80
	s_waitcnt vmcnt(12)
	v_pk_fma_f32 v[64:65], v[64:65], v[80:81], v[72:73] op_sel_hi:[1,0,1]
	v_fma_f32 v72, v88, s41, -v78
	v_exp_f32_e32 v72, v72
	v_pk_fma_f32 v[62:63], v[62:63], v[80:81], v[74:75] op_sel_hi:[1,0,1]
	v_add_f32_e32 v69, v80, v69
	s_waitcnt vmcnt(11)
	v_pk_fma_f32 v[58:59], v[58:59], v[72:73], v[62:63] op_sel_hi:[1,0,1]
	v_fma_f32 v62, v89, s41, -v78
	v_exp_f32_e32 v62, v62
	v_add_f32_e32 v69, v72, v69
	v_pk_fma_f32 v[60:61], v[60:61], v[72:73], v[64:65] op_sel_hi:[1,0,1]
	v_add_f32_e32 v63, v62, v69
	s_waitcnt vmcnt(10)
	v_pk_fma_f32 v[54:55], v[54:55], v[62:63], v[58:59] op_sel_hi:[1,0,1]
	v_fma_f32 v58, v90, s41, -v78
	v_exp_f32_e32 v58, v58
	v_pk_fma_f32 v[56:57], v[56:57], v[62:63], v[60:61] op_sel_hi:[1,0,1]
	v_add_f32_e32 v59, v58, v63
	s_waitcnt vmcnt(9)
	v_pk_fma_f32 v[50:51], v[50:51], v[58:59], v[54:55] op_sel_hi:[1,0,1]
	v_fma_f32 v54, v91, s41, -v78
	v_exp_f32_e32 v54, v54
	v_pk_fma_f32 v[52:53], v[52:53], v[58:59], v[56:57] op_sel_hi:[1,0,1]
	v_add_f32_e32 v55, v54, v59
	s_waitcnt vmcnt(8)
	v_pk_fma_f32 v[46:47], v[46:47], v[54:55], v[50:51] op_sel_hi:[1,0,1]
	v_fma_f32 v50, v92, s41, -v78
	v_exp_f32_e32 v50, v50
	v_pk_fma_f32 v[48:49], v[48:49], v[54:55], v[52:53] op_sel_hi:[1,0,1]
	v_add_f32_e32 v51, v50, v55
	s_waitcnt vmcnt(7)
	v_pk_fma_f32 v[42:43], v[42:43], v[50:51], v[46:47] op_sel_hi:[1,0,1]
	v_fma_f32 v46, v93, s41, -v78
	v_exp_f32_e32 v46, v46
	v_pk_fma_f32 v[44:45], v[44:45], v[50:51], v[48:49] op_sel_hi:[1,0,1]
	v_add_f32_e32 v47, v46, v51
	s_waitcnt vmcnt(6)
	v_pk_fma_f32 v[38:39], v[38:39], v[46:47], v[42:43] op_sel_hi:[1,0,1]
	v_fma_f32 v42, v94, s41, -v78
	v_exp_f32_e32 v42, v42
	v_pk_fma_f32 v[40:41], v[40:41], v[46:47], v[44:45] op_sel_hi:[1,0,1]
	v_add_f32_e32 v43, v42, v47
	s_waitcnt vmcnt(5)
	v_pk_fma_f32 v[34:35], v[34:35], v[42:43], v[38:39] op_sel_hi:[1,0,1]
	v_fma_f32 v38, v95, s41, -v78
	v_exp_f32_e32 v38, v38
	v_pk_fma_f32 v[36:37], v[36:37], v[42:43], v[40:41] op_sel_hi:[1,0,1]
	v_add_f32_e32 v39, v38, v43
	s_waitcnt vmcnt(4)
	v_pk_fma_f32 v[30:31], v[30:31], v[38:39], v[34:35] op_sel_hi:[1,0,1]
	v_fma_f32 v34, v96, s41, -v78
	v_exp_f32_e32 v34, v34
	v_pk_fma_f32 v[32:33], v[32:33], v[38:39], v[36:37] op_sel_hi:[1,0,1]
	v_add_f32_e32 v35, v34, v39
	s_waitcnt vmcnt(3)
	v_pk_fma_f32 v[26:27], v[26:27], v[34:35], v[30:31] op_sel_hi:[1,0,1]
	v_fma_f32 v30, v97, s41, -v78
	v_exp_f32_e32 v30, v30
	v_pk_fma_f32 v[28:29], v[28:29], v[34:35], v[32:33] op_sel_hi:[1,0,1]
	v_add_f32_e32 v31, v30, v35
	s_waitcnt vmcnt(2)
	v_pk_fma_f32 v[22:23], v[22:23], v[30:31], v[26:27] op_sel_hi:[1,0,1]
	v_fma_f32 v26, v98, s41, -v78
	v_exp_f32_e32 v26, v26
	v_pk_fma_f32 v[24:25], v[24:25], v[30:31], v[28:29] op_sel_hi:[1,0,1]
	v_add_f32_e32 v27, v26, v31
	s_waitcnt vmcnt(1)
	v_pk_fma_f32 v[18:19], v[18:19], v[26:27], v[22:23] op_sel_hi:[1,0,1]
	v_fma_f32 v22, v79, s41, -v78
	v_exp_f32_e32 v22, v22
	v_pk_fma_f32 v[20:21], v[20:21], v[26:27], v[24:25] op_sel_hi:[1,0,1]
	v_add_f32_e32 v69, v22, v27
	s_waitcnt vmcnt(0)
	v_pk_fma_f32 v[74:75], v[16:17], v[22:23], v[20:21] op_sel_hi:[1,0,1]
	v_pk_fma_f32 v[72:73], v[14:15], v[22:23], v[18:19] op_sel_hi:[1,0,1]
	s_cmp_eq_u32 s13, 0
	s_cbranch_scc0 .LBB0_347
	v_pk_mul_f32 v[8:9], v[8:9], v[12:13]
	v_pk_mul_f32 v[6:7], v[6:7], v[10:11]
	v_cmp_ge_u32_e32 vcc, s12, v67
	v_pk_mov_b32 v[10:11], v[6:7], v[8:9] op_sel:[1,0]
	v_mov_b32_e32 v7, v9
	v_pk_add_f32 v[6:7], v[10:11], v[6:7]
	s_nop 0
	v_add_f32_e32 v6, v6, v7
	v_mov_b32_e32 v7, 0xff800000
	s_nop 0
	v_add_f32_dpp v6, v6, v6 quad_perm:[1,0,3,2] row_mask:0xf bank_mask:0xf bound_ctrl:1
	s_nop 1
	v_add_f32_dpp v6, v6, v6 quad_perm:[2,3,0,1] row_mask:0xf bank_mask:0xf bound_ctrl:1
	s_nop 1
	v_add_f32_dpp v6, v6, v6 row_half_mirror row_mask:0xf bank_mask:0xf bound_ctrl:1
	s_nop 1
	v_add_f32_dpp v6, v6, v6 row_mirror row_mask:0xf bank_mask:0xf bound_ctrl:1
	v_mul_f32_e32 v6, 0x3e38aa3b, v6
	v_cndmask_b32_e32 v6, v7, v6, vcc
	v_mov_b32_e32 v7, v6
	v_mov_b32_e32 v8, v6
	s_nop 1
	v_permlane16_swap_b32_e32 v7, v8
	v_max_f32_e32 v8, v8, v8
	v_max_f32_e32 v7, v7, v7
	v_max_f32_e32 v7, v7, v8
	v_mov_b32_e32 v8, v7
	s_nop 1
	v_permlane32_swap_b32_e32 v7, v8
	v_max3_f32 v7, v78, v7, v8
	v_sub_f32_e32 v6, v6, v7
	v_exp_f32_e32 v10, v6
	v_sub_f32_e32 v6, v78, v7
	v_exp_f32_e32 v12, v6
	v_cmp_gt_u32_e32 vcc, 16, v190
	v_pk_mul_f32 v[2:3], v[2:3], v[10:11] op_sel_hi:[1,0]
	v_pk_mul_f32 v[4:5], v[4:5], v[10:11] op_sel_hi:[1,0]
	v_pk_fma_f32 v[2:3], v[72:73], v[12:13], v[2:3] op_sel_hi:[1,0,1]
	v_pk_fma_f32 v[14:15], v[74:75], v[12:13], v[4:5] op_sel_hi:[1,0,1]
	v_mov_b32_e32 v5, v3
	s_nop 1
	v_permlane16_swap_b32_e32 v3, v5
	v_fmac_f32_e32 v10, v69, v12
	v_mov_b32_e32 v4, v2
	v_add_f32_e32 v6, v3, v5
	v_mov_b32_e32 v3, v14
	v_mov_b32_e32 v7, v15
	v_mov_b32_e32 v11, v10
	v_permlane16_swap_b32_e32 v2, v4
	v_permlane16_swap_b32_e32 v14, v3
	v_permlane16_swap_b32_e32 v15, v7
	v_permlane16_swap_b32_e32 v10, v11
	v_add_f32_e32 v2, v2, v4
	v_add_f32_e32 v3, v14, v3
	v_add_f32_e32 v7, v15, v7
	v_add_f32_e32 v10, v10, v11
	v_mov_b32_e32 v4, v2
	v_mov_b32_e32 v8, v6
	v_mov_b32_e32 v5, v3
	v_mov_b32_e32 v9, v7
	v_mov_b32_e32 v11, v10
	v_permlane32_swap_b32_e32 v2, v4
	v_permlane32_swap_b32_e32 v6, v8
	v_permlane32_swap_b32_e32 v3, v5
	v_permlane32_swap_b32_e32 v7, v9
	v_permlane32_swap_b32_e32 v10, v11
	s_and_saveexec_b64 s[4:5], vcc
	v_readlane_b32 s20, v250, 10
	v_readlane_b32 s21, v250, 11
	s_cbranch_execz .LBB0_350
	v_add_f32_e32 v10, v10, v11
	v_div_scale_f32 v11, s[0:1], v10, v10, 1.0
	v_rcp_f32_e32 v12, v11
	v_div_scale_f32 v13, vcc, 1.0, v10, 1.0
	v_pk_add_f32 v[6:7], v[6:7], v[8:9]
	v_fma_f32 v14, -v11, v12, 1.0
	v_fmac_f32_e32 v12, v14, v12
	v_mul_f32_e32 v14, v13, v12
	v_fma_f32 v15, -v11, v14, v13
	v_fmac_f32_e32 v14, v15, v12
	v_fma_f32 v11, -v11, v14, v13
	v_div_fmas_f32 v11, v11, v12, v14
	v_div_fixup_f32 v10, v11, v10, 1.0
	v_pk_add_f32 v[2:3], v[2:3], v[4:5]
	v_pk_mul_f32 v[4:5], v[6:7], v[10:11] op_sel_hi:[1,0]
	v_pk_mul_f32 v[2:3], v[2:3], v[10:11] op_sel_hi:[1,0]
	v_mov_b32_e32 v6, 1
	v_and_b32_sdwa v7, v3, v6 dst_sel:DWORD dst_unused:UNUSED_PAD src0_sel:WORD_1 src1_sel:DWORD
	s_movk_i32 s0, 0x7fff
	v_and_b32_sdwa v8, v2, v6 dst_sel:DWORD dst_unused:UNUSED_PAD src0_sel:WORD_1 src1_sel:DWORD
	v_add3_u32 v3, v3, v7, s0
	v_and_b32_sdwa v7, v5, v6 dst_sel:DWORD dst_unused:UNUSED_PAD src0_sel:WORD_1 src1_sel:DWORD
	v_and_b32_sdwa v6, v4, v6 dst_sel:DWORD dst_unused:UNUSED_PAD src0_sel:WORD_1 src1_sel:DWORD
	v_add3_u32 v2, v2, v8, s0
	v_add3_u32 v5, v5, v7, s0
	v_add3_u32 v4, v4, v6, s0
	v_readlane_b32 s0, v250, 12
	v_readlane_b32 s1, v250, 13
	s_add_u32 s0, s0, s2
	s_addc_u32 s1, s1, s3
	s_lshl_b32 s2, s11, 1
	v_and_b32_e32 v5, 0xffff0000, v5
	v_and_b32_e32 v4, 0xffff0000, v4
	s_add_u32 s0, s0, s2
	v_or_b32_sdwa v3, v5, v3 dst_sel:DWORD dst_unused:UNUSED_PAD src0_sel:DWORD src1_sel:WORD_1
	v_or_b32_sdwa v2, v4, v2 dst_sel:DWORD dst_unused:UNUSED_PAD src0_sel:DWORD src1_sel:WORD_1
	s_addc_u32 s1, s1, 0
	v_lshlrev_b32_e32 v4, 1, v66
	global_store_dwordx2 v4, v[2:3], s[0:1] offset:1024
